# non-temporal policy (nt) on the prologue phase's once-read f32 input loads (x rows and weight tiles), on top of the QK loop rewrite
# speedup vs baseline: 1.0121x; 1.0021x over previous
; __device__ __forceinline__ int orig_wgu(int np) { const int T = np >> 8, cl = np & 255; return ((cl >> 7) ? DFF : 0) + 128 * T + (cl & 127); }
; template <int MODE> __device__ __forceinline__ void wt_item(const float* W, int K, int N, int Np, const float* gain, bf16_t* WT, int item, float* scr, int lane) {
;     const int nblk = Np / 32, kb = item / nblk, nb = item - kb * nblk, k0 = 64 * kb, n0 = 32 * nb;
;     const int np = n0 + (lane & 31); const int o = (MODE == 1) ? orig_win(np) : (MODE == 2) ? orig_wgu(np) : np;
;     float wv[32];
; #pragma unroll
;     for (int i = 0; i < 32; ++i) { const int kk = 2 * i + (lane >> 5); wv[i] = (o >= 0) ? W[(size_t)(k0 + kk) * N + o] : 0.f; }
; __device__ __forceinline__ void ph0_prologue(const Ctx& C, unsigned char* lds) {
;     ...
;     for (int it = gw; it < NIT; it += NGW) {
;         int r = __builtin_amdgcn_readfirstlane(it);
;         if (r < I_IN) { wt_item<1>(C.w_in, DM, DIN, DINP, C.g_mix, (bf16_t*)(C.ws + WS_WIN), r, scr, C.lane); continue; } r -= I_IN;
;         if (r < I_OUT) { wt_item<0>(C.w_out, DM, DM, DM, nullptr, (bf16_t*)(C.ws + WS_WOUT), r, scr, C.lane); continue; } r -= I_OUT;
;         if (r < I_Q) { wt_item<0>(C.w_q, DM, DM, DM, C.g_mem, (bf16_t*)(C.ws + WS_WQ), r, scr, C.lane); continue; } r -= I_Q;
;         if (r < I_KV) { wt_item<0>(C.w_kv, DM, 2 * DM, 2 * DM, C.g_mem_src, (bf16_t*)(C.ws + WS_WKV), r, scr, C.lane); continue; } r -= I_KV;
;         if (r < I_O) { wt_item<0>(C.w_o, DM, DM, DM, nullptr, (bf16_t*)(C.ws + WS_WO), r, scr, C.lane); continue; } r -= I_O;
;         if (r < I_GU) { wt_item<2>(C.w_gu, DM, 2 * DFF, 2 * DFF, C.g_ffn, (bf16_t*)(C.ws + WS_WGU), r, scr, C.lane); continue; } r -= I_GU;
;         wt_item<0>(C.w_down, DFF, DM, DM, nullptr, (bf16_t*)(C.ws + WS_WDOWN), r, scr, C.lane);
.LBB0_13:
	s_cmpk_gt_u32 s20, 0x97f
	s_cbranch_scc0 .LBB0_101
	s_cmpk_gt_u32 s20, 0xb7f
	s_cbranch_scc0 .LBB0_96
	s_cmpk_gt_u32 s20, 0xf7f
	s_cbranch_scc0 .LBB0_91
	s_cmpk_gt_u32 s20, 0x117f
	s_cbranch_scc0 .LBB0_88
	s_cmpk_gt_u32 s20, 0x1c7f
	s_cbranch_scc0 .LBB0_19
	s_lshl_b32 s6, s20, 1
	s_andn2_b32 s6, s6, 63
	s_add_i32 s8, s6, 0xffffc700
	s_lshl_b32 s6, s20, 5
	s_and_b32 s6, s6, 0x3e0
	v_add_u32_e32 v16, s8, v52
	v_or_b32_e32 v0, s6, v67
	v_readlane_b32 s24, v250, 0
	v_add_u32_e32 v22, 2, v16
	v_add_u32_e32 v24, 4, v16
	v_add_u32_e32 v26, 6, v16
	v_add_u32_e32 v28, 8, v16
	v_add_u32_e32 v30, 10, v16
	v_add_u32_e32 v32, 12, v16
	v_add_u32_e32 v34, 14, v16
	v_lshlrev_b32_e32 v0, 2, v0
	v_readlane_b32 s25, v250, 1
	v_ashrrev_i32_e32 v17, 31, v16
	v_ashrrev_i32_e32 v23, 31, v22
	v_ashrrev_i32_e32 v25, 31, v24
	v_ashrrev_i32_e32 v27, 31, v26
	v_ashrrev_i32_e32 v29, 31, v28
	v_ashrrev_i32_e32 v31, 31, v30
	v_ashrrev_i32_e32 v33, 31, v32
	v_ashrrev_i32_e32 v35, 31, v34
	v_lshl_add_u64 v[18:19], s[24:25], 0, v[0:1]
	v_lshlrev_b64 v[20:21], 12, v[16:17]
	v_lshlrev_b64 v[22:23], 12, v[22:23]
	v_lshlrev_b64 v[24:25], 12, v[24:25]
	v_lshlrev_b64 v[26:27], 12, v[26:27]
	v_lshlrev_b64 v[28:29], 12, v[28:29]
	v_lshlrev_b64 v[30:31], 12, v[30:31]
	v_lshlrev_b64 v[32:33], 12, v[32:33]
	v_lshlrev_b64 v[34:35], 12, v[34:35]
	v_lshl_add_u64 v[20:21], v[18:19], 0, v[20:21]
	v_lshl_add_u64 v[22:23], v[18:19], 0, v[22:23]
	v_lshl_add_u64 v[24:25], v[18:19], 0, v[24:25]
	v_lshl_add_u64 v[26:27], v[18:19], 0, v[26:27]
	v_lshl_add_u64 v[28:29], v[18:19], 0, v[28:29]
	v_lshl_add_u64 v[30:31], v[18:19], 0, v[30:31]
	v_lshl_add_u64 v[32:33], v[18:19], 0, v[32:33]
	v_lshl_add_u64 v[34:35], v[18:19], 0, v[34:35]
	global_load_dword v0, v[20:21], off nt
	global_load_dword v36, v[22:23], off nt
	global_load_dword v37, v[24:25], off nt
	global_load_dword v38, v[26:27], off nt
	global_load_dword v39, v[28:29], off nt
	global_load_dword v40, v[30:31], off nt
	global_load_dword v41, v[32:33], off nt
	global_load_dword v42, v[34:35], off nt
	v_add_u32_e32 v20, 16, v16
	v_add_u32_e32 v22, 18, v16
	v_add_u32_e32 v24, 20, v16
	v_add_u32_e32 v26, 22, v16
	v_add_u32_e32 v28, 24, v16
	v_add_u32_e32 v30, 26, v16
	v_add_u32_e32 v32, 28, v16
	v_add_u32_e32 v34, 30, v16
	v_ashrrev_i32_e32 v21, 31, v20
	v_ashrrev_i32_e32 v23, 31, v22
	v_ashrrev_i32_e32 v25, 31, v24
	v_ashrrev_i32_e32 v27, 31, v26
	v_ashrrev_i32_e32 v29, 31, v28
	v_ashrrev_i32_e32 v31, 31, v30
	v_ashrrev_i32_e32 v33, 31, v32
	v_ashrrev_i32_e32 v35, 31, v34
	v_lshlrev_b64 v[20:21], 12, v[20:21]
	v_lshlrev_b64 v[22:23], 12, v[22:23]
	v_lshlrev_b64 v[24:25], 12, v[24:25]
	v_lshlrev_b64 v[26:27], 12, v[26:27]
	v_lshlrev_b64 v[28:29], 12, v[28:29]
	v_lshlrev_b64 v[30:31], 12, v[30:31]
	v_lshlrev_b64 v[32:33], 12, v[32:33]
	v_lshlrev_b64 v[34:35], 12, v[34:35]
	v_lshl_add_u64 v[20:21], v[18:19], 0, v[20:21]
	v_lshl_add_u64 v[22:23], v[18:19], 0, v[22:23]
	v_lshl_add_u64 v[24:25], v[18:19], 0, v[24:25]
	v_lshl_add_u64 v[26:27], v[18:19], 0, v[26:27]
	v_lshl_add_u64 v[28:29], v[18:19], 0, v[28:29]
	v_lshl_add_u64 v[30:31], v[18:19], 0, v[30:31]
	v_lshl_add_u64 v[32:33], v[18:19], 0, v[32:33]
	v_lshl_add_u64 v[34:35], v[18:19], 0, v[34:35]
	global_load_dword v43, v[20:21], off nt
	global_load_dword v44, v[22:23], off nt
	global_load_dword v45, v[24:25], off nt
	global_load_dword v46, v[26:27], off nt
	global_load_dword v47, v[28:29], off nt
	global_load_dword v48, v[30:31], off nt
	global_load_dword v49, v[32:33], off nt
	global_load_dword v50, v[34:35], off nt
	v_add_u32_e32 v20, 32, v16
	v_add_u32_e32 v22, 34, v16
	v_add_u32_e32 v24, 36, v16
	v_add_u32_e32 v26, 38, v16
	v_add_u32_e32 v28, 40, v16
	v_add_u32_e32 v30, 42, v16
	v_add_u32_e32 v32, 44, v16
	v_add_u32_e32 v34, 46, v16
	v_ashrrev_i32_e32 v21, 31, v20
	v_ashrrev_i32_e32 v23, 31, v22
	v_ashrrev_i32_e32 v25, 31, v24
	v_ashrrev_i32_e32 v27, 31, v26
	v_ashrrev_i32_e32 v29, 31, v28
	v_ashrrev_i32_e32 v31, 31, v30
	v_ashrrev_i32_e32 v33, 31, v32
	v_ashrrev_i32_e32 v35, 31, v34
	v_lshlrev_b64 v[20:21], 12, v[20:21]
	v_lshlrev_b64 v[22:23], 12, v[22:23]
	v_lshlrev_b64 v[24:25], 12, v[24:25]
	v_lshlrev_b64 v[26:27], 12, v[26:27]
	v_lshlrev_b64 v[28:29], 12, v[28:29]
	v_lshlrev_b64 v[30:31], 12, v[30:31]
	v_lshlrev_b64 v[32:33], 12, v[32:33]
	v_lshlrev_b64 v[34:35], 12, v[34:35]
	v_lshl_add_u64 v[20:21], v[18:19], 0, v[20:21]
	v_lshl_add_u64 v[22:23], v[18:19], 0, v[22:23]
	v_lshl_add_u64 v[24:25], v[18:19], 0, v[24:25]
	v_lshl_add_u64 v[26:27], v[18:19], 0, v[26:27]
	v_lshl_add_u64 v[28:29], v[18:19], 0, v[28:29]
	v_lshl_add_u64 v[30:31], v[18:19], 0, v[30:31]
	v_lshl_add_u64 v[32:33], v[18:19], 0, v[32:33]
	v_lshl_add_u64 v[34:35], v[18:19], 0, v[34:35]
	global_load_dword v51, v[20:21], off nt
	global_load_dword v74, v[22:23], off nt
	global_load_dword v75, v[24:25], off nt
	global_load_dword v76, v[26:27], off nt
	global_load_dword v77, v[28:29], off nt
	global_load_dword v78, v[30:31], off nt
	global_load_dword v79, v[32:33], off nt
	s_nop 0
	global_load_dword v34, v[34:35], off nt
	v_add_u32_e32 v20, 48, v16
	v_add_u32_e32 v22, 50, v16
	v_add_u32_e32 v24, 52, v16
	v_add_u32_e32 v26, 54, v16
	v_add_u32_e32 v28, 56, v16
	v_add_u32_e32 v30, 58, v16
	v_add_u32_e32 v32, 60, v16
	v_add_u32_e32 v16, 62, v16
	v_ashrrev_i32_e32 v21, 31, v20
	v_ashrrev_i32_e32 v23, 31, v22
	v_ashrrev_i32_e32 v25, 31, v24
	v_ashrrev_i32_e32 v17, 31, v16
	v_lshlrev_b64 v[20:21], 12, v[20:21]
	v_lshlrev_b64 v[22:23], 12, v[22:23]
	v_lshlrev_b64 v[24:25], 12, v[24:25]
	v_ashrrev_i32_e32 v27, 31, v26
	v_ashrrev_i32_e32 v29, 31, v28
	v_ashrrev_i32_e32 v31, 31, v30
	v_ashrrev_i32_e32 v33, 31, v32
	v_lshlrev_b64 v[16:17], 12, v[16:17]
	v_lshl_add_u64 v[20:21], v[18:19], 0, v[20:21]
	v_lshl_add_u64 v[22:23], v[18:19], 0, v[22:23]
	v_lshl_add_u64 v[24:25], v[18:19], 0, v[24:25]
	v_lshlrev_b64 v[26:27], 12, v[26:27]
	v_lshlrev_b64 v[28:29], 12, v[28:29]
	v_lshlrev_b64 v[30:31], 12, v[30:31]
	v_lshlrev_b64 v[32:33], 12, v[32:33]
	v_lshl_add_u64 v[16:17], v[18:19], 0, v[16:17]
	v_lshl_add_u64 v[26:27], v[18:19], 0, v[26:27]
	v_lshl_add_u64 v[28:29], v[18:19], 0, v[28:29]
	v_lshl_add_u64 v[30:31], v[18:19], 0, v[30:31]
	v_lshl_add_u64 v[32:33], v[18:19], 0, v[32:33]
	global_load_dword v18, v[20:21], off nt
	global_load_dword v19, v[22:23], off nt
	s_nop 0
	global_load_dword v20, v[24:25], off nt
	global_load_dword v21, v[26:27], off nt
	global_load_dword v22, v[28:29], off nt
	global_load_dword v23, v[30:31], off nt
	s_nop 0
	global_load_dword v24, v[32:33], off nt
	s_nop 0
	global_load_dword v16, v[16:17], off nt
	s_waitcnt vmcnt(30)
; __device__ __forceinline__ unsigned cvt_pk_bf16(float lo, float hi) { unsigned r; asm volatile("v_cvt_pk_bf16_f32 %0, %1, %2" : "=v"(r) : "v"(lo), "v"(hi)); return r; }
; #define LDS_WAIT() asm volatile("s_waitcnt lgkmcnt(0)" ::: "memory")
; __device__ __forceinline__ int orig_wgu(int np) { const int T = np >> 8, cl = np & 255; return ((cl >> 7) ? DFF : 0) + 128 * T + (cl & 127); }
; template <int MODE> __device__ __forceinline__ void wt_item(const float* W, int K, int N, int Np, const float* gain, bf16_t* WT, int item, float* scr, int lane) {
;     const int nblk = Np / 32, kb = item / nblk, nb = item - kb * nblk, k0 = 64 * kb, n0 = 32 * nb;
;     const int np = n0 + (lane & 31); const int o = (MODE == 1) ? orig_win(np) : (MODE == 2) ? orig_wgu(np) : np;
;     float wv[32];
; #pragma unroll
;     for (int i = 0; i < 32; ++i) { const int kk = 2 * i + (lane >> 5); wv[i] = (o >= 0) ? W[(size_t)(k0 + kk) * N + o] : 0.f; }
;     ...
;     for (int i = 0; i < 32; ++i) scr[(2 * i + (lane >> 5)) * 33 + (lane & 31)] = wv[i];
;     LDS_WAIT();
;     const int c = lane & 7;
; #pragma unroll
;     for (int j = 0; j < 4; ++j) { const int n = (lane >> 3) + 8 * j; const float* s = scr + (8 * c) * 33 + n;
;         u32x4 ov; ov.x = cvt_pk_bf16(s[0 * 33], s[1 * 33]); ov.y = cvt_pk_bf16(s[2 * 33], s[3 * 33]); ov.z = cvt_pk_bf16(s[4 * 33], s[5 * 33]); ov.w = cvt_pk_bf16(s[6 * 33], s[7 * 33]);
;         *(u32x4*)(WT + (size_t)(n0 + n) * K + k0 + 8 * c) = ov; }
;     LDS_WAIT();
; }
	ds_write2_b32 v53, v0, v36 offset1:66
	s_waitcnt vmcnt(28)
	ds_write2_b32 v53, v37, v38 offset0:132 offset1:198
	s_waitcnt vmcnt(26)
	ds_write2_b32 v61, v39, v40 offset0:8 offset1:74
	s_waitcnt vmcnt(24)
	ds_write2_b32 v61, v41, v42 offset0:140 offset1:206
	s_waitcnt vmcnt(22)
	ds_write2_b32 v62, v43, v44 offset0:16 offset1:82
	s_waitcnt vmcnt(20)
	ds_write2_b32 v62, v45, v46 offset0:148 offset1:214
	s_waitcnt vmcnt(18)
	ds_write2_b32 v63, v47, v48 offset0:24 offset1:90
	s_waitcnt vmcnt(16)
	ds_write2_b32 v63, v49, v50 offset0:156 offset1:222
	s_waitcnt vmcnt(14)
	ds_write2_b32 v65, v51, v74 offset0:32 offset1:98
	s_waitcnt vmcnt(12)
	ds_write2_b32 v65, v75, v76 offset0:164 offset1:230
	s_waitcnt vmcnt(10)
	ds_write2_b32 v68, v77, v78 offset0:40 offset1:106
	s_waitcnt vmcnt(8)
	ds_write2_b32 v68, v79, v34 offset0:172 offset1:238
	s_waitcnt vmcnt(6)
	ds_write2_b32 v69, v18, v19 offset0:48 offset1:114
	s_waitcnt vmcnt(4)
	ds_write2_b32 v69, v20, v21 offset0:180 offset1:246
	s_waitcnt vmcnt(2)
	ds_write2_b32 v70, v22, v23 offset0:56 offset1:122
	s_waitcnt vmcnt(0)
	ds_write2_b32 v70, v24, v16 offset0:188 offset1:254
	s_waitcnt lgkmcnt(0)
	ds_read2_b32 v[16:17], v55 offset1:33
	s_waitcnt lgkmcnt(0)
	v_cvt_pk_bf16_f32 v16, v16, v17
	ds_read2_b32 v[18:19], v55 offset0:66 offset1:99
	s_waitcnt lgkmcnt(0)
	v_cvt_pk_bf16_f32 v17, v18, v19
	ds_read2_b32 v[18:19], v55 offset0:132 offset1:165
	v_lshl_add_u64 v[22:23], s[8:9], 1, v[2:3]
	v_add_u32_e32 v0, s6, v54
	s_waitcnt lgkmcnt(0)
	v_cvt_pk_bf16_f32 v18, v18, v19
	ds_read2_b32 v[20:21], v55 offset0:198 offset1:231
	s_waitcnt lgkmcnt(0)
	v_cvt_pk_bf16_f32 v19, v20, v21
	v_mad_i64_i32 v[24:25], s[16:17], v0, s2, v[22:23]
	ds_read2_b32 v[20:21], v55 offset0:8 offset1:41
	global_store_dwordx4 v[24:25], v[16:19], off
	v_add_u32_e32 v0, s6, v56
	v_mad_i64_i32 v[24:25], s[16:17], v0, s2, v[22:23]
	s_waitcnt lgkmcnt(0)
	v_cvt_pk_bf16_f32 v16, v20, v21
	ds_read2_b32 v[18:19], v55 offset0:74 offset1:107
	s_waitcnt lgkmcnt(0)
	v_cvt_pk_bf16_f32 v17, v18, v19
	ds_read2_b32 v[18:19], v55 offset0:140 offset1:173
	s_waitcnt lgkmcnt(0)
	v_cvt_pk_bf16_f32 v18, v18, v19
	ds_read2_b32 v[20:21], v55 offset0:206 offset1:239
	s_waitcnt lgkmcnt(0)
	v_cvt_pk_bf16_f32 v19, v20, v21
	ds_read2_b32 v[20:21], v55 offset0:16 offset1:49
	global_store_dwordx4 v[24:25], v[16:19], off
	v_add_u32_e32 v0, s6, v57
	v_mad_i64_i32 v[24:25], s[16:17], v0, s2, v[22:23]
	s_waitcnt lgkmcnt(0)
	v_cvt_pk_bf16_f32 v16, v20, v21
	ds_read2_b32 v[18:19], v55 offset0:82 offset1:115
	s_waitcnt lgkmcnt(0)
	v_cvt_pk_bf16_f32 v17, v18, v19
	ds_read2_b32 v[18:19], v55 offset0:148 offset1:181
	s_waitcnt lgkmcnt(0)
	v_cvt_pk_bf16_f32 v18, v18, v19
	ds_read2_b32 v[20:21], v55 offset0:214 offset1:247
	s_waitcnt lgkmcnt(0)
	v_cvt_pk_bf16_f32 v19, v20, v21
	ds_read2_b32 v[20:21], v55 offset0:24 offset1:57
	global_store_dwordx4 v[24:25], v[16:19], off
	v_add_u32_e32 v0, s6, v58
	v_readlane_b32 s26, v250, 2
	s_waitcnt lgkmcnt(0)
	v_cvt_pk_bf16_f32 v16, v20, v21
	ds_read2_b32 v[18:19], v55 offset0:90 offset1:123
	s_waitcnt lgkmcnt(0)
	v_cvt_pk_bf16_f32 v17, v18, v19
	ds_read2_b32 v[18:19], v55 offset0:156 offset1:189
	s_waitcnt lgkmcnt(0)
	v_cvt_pk_bf16_f32 v18, v18, v19
	ds_read2_b32 v[20:21], v55 offset0:222 offset1:255
	s_waitcnt lgkmcnt(0)
	v_cvt_pk_bf16_f32 v19, v20, v21
	v_mad_i64_i32 v[20:21], s[6:7], v0, s2, v[22:23]
	global_store_dwordx4 v[20:21], v[16:19], off
	s_waitcnt lgkmcnt(0)
	v_readlane_b32 s27, v250, 3
	v_readlane_b32 s28, v250, 4
	v_readlane_b32 s29, v250, 5
	v_readlane_b32 s30, v250, 6
	v_readlane_b32 s31, v250, 7
	s_mov_b64 s[6:7], 0
.LBB0_19:
	s_andn2_b64 vcc, exec, s[6:7]
	s_cbranch_vccnz .LBB0_87
	s_add_i32 s6, s20, 0xffffee80
	s_mul_i32 s7, s6, 0xba2f
	s_lshr_b32 s7, s7, 23
	s_mul_i32 s8, s7, 0xffffff50
	s_add_i32 s6, s8, s6
	s_lshl_b32 s8, s7, 6
	s_lshl_b32 s21, s6, 5
	s_bfe_i32 s7, s20, 0x10002
	s_lshl_b32 s6, s6, 4
	s_and_b32 s7, s7, 0xb00
	s_and_b32 s6, s6, 0xffffff80
	s_add_i32 s6, s6, s7
	s_and_b32 s7, s21, 0x60
	v_or_b32_e32 v0, s7, v67
	v_readlane_b32 s24, v250, 8
	v_or_b32_e32 v0, s6, v0
	s_cmp_gt_i32 s6, -1
	v_readlane_b32 s26, v250, 10
	v_readlane_b32 s27, v250, 11
	s_cselect_b64 s[16:17], -1, 0
	s_cmp_lt_i32 s6, 0
	v_add_u32_e32 v38, s8, v52
	v_lshl_add_u64 v[42:43], v[0:1], 2, s[26:27]
	v_mov_b32_e32 v17, 0
	v_mov_b32_e32 v16, 0
	v_readlane_b32 s25, v250, 9
	v_readlane_b32 s28, v250, 12
	v_readlane_b32 s29, v250, 13
	v_readlane_b32 s30, v250, 14
	v_readlane_b32 s31, v250, 15
	s_cbranch_scc1 .LBB0_22
	v_mad_i64_i32 v[18:19], s[6:7], v38, s3, v[42:43]
	global_load_dword v16, v[18:19], off nt
.LBB0_22:
	v_cndmask_b32_e64 v0, 0, 1, s[16:17]
	v_cmp_ne_u32_e64 s[6:7], 1, v0
	s_andn2_b64 vcc, exec, s[16:17]
	s_cbranch_vccnz .LBB0_24
	v_add_u32_e32 v0, 2, v38
	v_mad_i64_i32 v[18:19], s[16:17], v0, s3, v[42:43]
	global_load_dword v17, v[18:19], off nt
.LBB0_24:
	v_mov_b32_e32 v19, 0
	s_and_b64 vcc, exec, s[6:7]
	v_mov_b32_e32 v18, 0
	s_cbranch_vccnz .LBB0_26
	v_add_u32_e32 v0, 4, v38
	v_mad_i64_i32 v[20:21], s[16:17], v0, s3, v[42:43]
	global_load_dword v18, v[20:21], off nt
.LBB0_26:
	s_and_b64 vcc, exec, s[6:7]
	s_cbranch_vccnz .LBB0_28
	v_add_u32_e32 v0, 6, v38
	v_mad_i64_i32 v[20:21], s[16:17], v0, s3, v[42:43]
	global_load_dword v19, v[20:21], off nt
.LBB0_28:
	v_mov_b32_e32 v21, 0
	s_and_b64 vcc, exec, s[6:7]
	v_mov_b32_e32 v20, 0
	s_cbranch_vccnz .LBB0_30
	v_add_u32_e32 v0, 8, v38
	v_mad_i64_i32 v[22:23], s[16:17], v0, s3, v[42:43]
	global_load_dword v20, v[22:23], off nt
.LBB0_30:
	s_and_b64 vcc, exec, s[6:7]
	s_cbranch_vccnz .LBB0_32
	v_add_u32_e32 v0, 10, v38
	v_mad_i64_i32 v[22:23], s[16:17], v0, s3, v[42:43]
	global_load_dword v21, v[22:23], off nt
; __device__ __forceinline__ int orig_wgu(int np) { const int T = np >> 8, cl = np & 255; return ((cl >> 7) ? DFF : 0) + 128 * T + (cl & 127); }
; template <int MODE> __device__ __forceinline__ void wt_item(const float* W, int K, int N, int Np, const float* gain, bf16_t* WT, int item, float* scr, int lane) {
;     const int nblk = Np / 32, kb = item / nblk, nb = item - kb * nblk, k0 = 64 * kb, n0 = 32 * nb;
;     const int np = n0 + (lane & 31); const int o = (MODE == 1) ? orig_win(np) : (MODE == 2) ? orig_wgu(np) : np;
;     float wv[32];
; #pragma unroll
;     for (int i = 0; i < 32; ++i) { const int kk = 2 * i + (lane >> 5); wv[i] = (o >= 0) ? W[(size_t)(k0 + kk) * N + o] : 0.f; }
.LBB0_32:
	v_mov_b32_e32 v23, 0
	s_and_b64 vcc, exec, s[6:7]
	v_mov_b32_e32 v22, 0
	s_cbranch_vccnz .LBB0_34
	v_add_u32_e32 v0, 12, v38
	v_mad_i64_i32 v[24:25], s[16:17], v0, s3, v[42:43]
	global_load_dword v22, v[24:25], off nt
.LBB0_34:
	s_and_b64 vcc, exec, s[6:7]
	s_cbranch_vccnz .LBB0_36
	v_add_u32_e32 v0, 14, v38
	v_mad_i64_i32 v[24:25], s[16:17], v0, s3, v[42:43]
	global_load_dword v23, v[24:25], off nt
.LBB0_36:
	v_mov_b32_e32 v25, 0
	s_and_b64 vcc, exec, s[6:7]
	v_mov_b32_e32 v24, 0
	s_cbranch_vccnz .LBB0_38
	v_add_u32_e32 v0, 16, v38
	v_mad_i64_i32 v[26:27], s[16:17], v0, s3, v[42:43]
	global_load_dword v24, v[26:27], off nt
.LBB0_38:
	s_and_b64 vcc, exec, s[6:7]
	s_cbranch_vccnz .LBB0_40
	v_add_u32_e32 v0, 18, v38
	v_mad_i64_i32 v[26:27], s[16:17], v0, s3, v[42:43]
	global_load_dword v25, v[26:27], off nt
.LBB0_40:
	v_mov_b32_e32 v27, 0
	s_and_b64 vcc, exec, s[6:7]
	v_mov_b32_e32 v26, 0
	s_cbranch_vccnz .LBB0_42
	v_add_u32_e32 v0, 20, v38
	v_mad_i64_i32 v[28:29], s[16:17], v0, s3, v[42:43]
	global_load_dword v26, v[28:29], off nt
.LBB0_42:
	s_and_b64 vcc, exec, s[6:7]
	s_cbranch_vccnz .LBB0_44
	v_add_u32_e32 v0, 22, v38
	v_mad_i64_i32 v[28:29], s[16:17], v0, s3, v[42:43]
	global_load_dword v27, v[28:29], off nt
.LBB0_44:
	v_mov_b32_e32 v29, 0
	s_and_b64 vcc, exec, s[6:7]
	v_mov_b32_e32 v28, 0
	s_cbranch_vccnz .LBB0_46
	v_add_u32_e32 v0, 24, v38
	v_mad_i64_i32 v[30:31], s[16:17], v0, s3, v[42:43]
	global_load_dword v28, v[30:31], off nt
.LBB0_46:
	s_and_b64 vcc, exec, s[6:7]
	s_cbranch_vccnz .LBB0_48
	v_add_u32_e32 v0, 26, v38
	v_mad_i64_i32 v[30:31], s[16:17], v0, s3, v[42:43]
	global_load_dword v29, v[30:31], off nt
.LBB0_48:
	v_mov_b32_e32 v31, 0
	s_and_b64 vcc, exec, s[6:7]
	v_mov_b32_e32 v30, 0
	s_cbranch_vccnz .LBB0_50
	v_add_u32_e32 v0, 28, v38
	v_mad_i64_i32 v[32:33], s[16:17], v0, s3, v[42:43]
	global_load_dword v30, v[32:33], off nt
.LBB0_50:
	s_and_b64 vcc, exec, s[6:7]
	s_cbranch_vccnz .LBB0_52
	v_add_u32_e32 v0, 30, v38
	v_mad_i64_i32 v[32:33], s[16:17], v0, s3, v[42:43]
	global_load_dword v31, v[32:33], off nt
.LBB0_52:
	v_mov_b32_e32 v33, 0
	s_and_b64 vcc, exec, s[6:7]
	v_mov_b32_e32 v32, 0
	s_cbranch_vccnz .LBB0_54
	v_add_u32_e32 v0, 32, v38
	v_mad_i64_i32 v[34:35], s[16:17], v0, s3, v[42:43]
	global_load_dword v32, v[34:35], off nt
.LBB0_54:
	s_and_b64 vcc, exec, s[6:7]
	s_cbranch_vccnz .LBB0_56
	v_add_u32_e32 v0, 34, v38
	v_mad_i64_i32 v[34:35], s[16:17], v0, s3, v[42:43]
	global_load_dword v33, v[34:35], off nt
.LBB0_56:
	v_mov_b32_e32 v35, 0
	s_and_b64 vcc, exec, s[6:7]
	v_mov_b32_e32 v34, 0
	s_cbranch_vccnz .LBB0_58
	v_add_u32_e32 v0, 36, v38
	v_mad_i64_i32 v[36:37], s[16:17], v0, s3, v[42:43]
	global_load_dword v34, v[36:37], off nt
.LBB0_58:
	s_and_b64 vcc, exec, s[6:7]
	s_cbranch_vccnz .LBB0_60
	v_add_u32_e32 v0, 38, v38
	v_mad_i64_i32 v[36:37], s[16:17], v0, s3, v[42:43]
	global_load_dword v35, v[36:37], off nt
.LBB0_60:
	v_mov_b32_e32 v37, 0
	s_and_b64 vcc, exec, s[6:7]
	v_mov_b32_e32 v36, 0
	s_cbranch_vccnz .LBB0_62
	v_add_u32_e32 v0, 40, v38
	v_mad_i64_i32 v[40:41], s[16:17], v0, s3, v[42:43]
	global_load_dword v36, v[40:41], off nt
.LBB0_62:
	s_and_b64 vcc, exec, s[6:7]
	s_cbranch_vccnz .LBB0_64
	v_add_u32_e32 v0, 42, v38
	v_mad_i64_i32 v[40:41], s[16:17], v0, s3, v[42:43]
	global_load_dword v37, v[40:41], off nt
.LBB0_64:
	v_mov_b32_e32 v41, 0
	s_and_b64 vcc, exec, s[6:7]
	v_mov_b32_e32 v40, 0
	s_cbranch_vccnz .LBB0_66
	v_add_u32_e32 v0, 44, v38
	v_mad_i64_i32 v[44:45], s[16:17], v0, s3, v[42:43]
	global_load_dword v40, v[44:45], off nt
.LBB0_66:
	s_and_b64 vcc, exec, s[6:7]
	s_cbranch_vccnz .LBB0_68
	v_add_u32_e32 v0, 46, v38
	v_mad_i64_i32 v[44:45], s[16:17], v0, s3, v[42:43]
	global_load_dword v41, v[44:45], off nt
.LBB0_68:
	v_mov_b32_e32 v45, 0
	s_and_b64 vcc, exec, s[6:7]
	v_mov_b32_e32 v44, 0
	s_cbranch_vccnz .LBB0_70
	v_add_u32_e32 v0, 48, v38
	v_mad_i64_i32 v[46:47], s[16:17], v0, s3, v[42:43]
	global_load_dword v44, v[46:47], off nt
.LBB0_70:
	s_and_b64 vcc, exec, s[6:7]
	s_cbranch_vccnz .LBB0_72
	v_add_u32_e32 v0, 50, v38
	v_mad_i64_i32 v[46:47], s[16:17], v0, s3, v[42:43]
	global_load_dword v45, v[46:47], off nt
; template <int MODE> __device__ __forceinline__ void wt_item(const float* W, int K, int N, int Np, const float* gain, bf16_t* WT, int item, float* scr, int lane) {
;     ...
;     for (int i = 0; i < 32; ++i) { const int kk = 2 * i + (lane >> 5); wv[i] = (o >= 0) ? W[(size_t)(k0 + kk) * N + o] : 0.f; }
;     if (gain) {
;         float gv[32];
; #pragma unroll
;         for (int i = 0; i < 32; ++i) gv[i] = gain[k0 + 2 * i + (lane >> 5)];
; #pragma unroll
;         for (int i = 0; i < 32; ++i) wv[i] *= gv[i];
.LBB0_72:
	v_mov_b32_e32 v47, 0
	s_and_b64 vcc, exec, s[6:7]
	v_mov_b32_e32 v46, 0
	s_cbranch_vccnz .LBB0_74
	v_add_u32_e32 v0, 52, v38
	v_mad_i64_i32 v[48:49], s[16:17], v0, s3, v[42:43]
	global_load_dword v46, v[48:49], off nt
.LBB0_74:
	s_and_b64 vcc, exec, s[6:7]
	s_cbranch_vccnz .LBB0_76
	v_add_u32_e32 v0, 54, v38
	v_mad_i64_i32 v[48:49], s[16:17], v0, s3, v[42:43]
	global_load_dword v47, v[48:49], off nt
.LBB0_76:
	v_mov_b32_e32 v49, 0
	s_and_b64 vcc, exec, s[6:7]
	v_mov_b32_e32 v48, 0
	s_cbranch_vccnz .LBB0_78
	v_add_u32_e32 v0, 56, v38
	v_mad_i64_i32 v[50:51], s[16:17], v0, s3, v[42:43]
	global_load_dword v48, v[50:51], off nt
.LBB0_78:
	s_and_b64 vcc, exec, s[6:7]
	s_cbranch_vccnz .LBB0_80
	v_add_u32_e32 v0, 58, v38
	v_mad_i64_i32 v[50:51], s[16:17], v0, s3, v[42:43]
	global_load_dword v49, v[50:51], off nt
.LBB0_80:
	v_mov_b32_e32 v51, 0
	s_and_b64 vcc, exec, s[6:7]
	v_mov_b32_e32 v50, 0
	s_cbranch_vccnz .LBB0_82
	v_add_u32_e32 v0, 60, v38
	v_mad_i64_i32 v[74:75], s[16:17], v0, s3, v[42:43]
	global_load_dword v50, v[74:75], off nt
.LBB0_82:
	s_and_b64 vcc, exec, s[6:7]
	s_cbranch_vccnz .LBB0_84
	v_add_u32_e32 v0, 62, v38
	v_mad_i64_i32 v[42:43], s[6:7], v0, s3, v[42:43]
	global_load_dword v51, v[42:43], off nt
.LBB0_84:
	s_andn2_b64 vcc, exec, s[10:11]
	s_cbranch_vccnz .LBB0_86
	v_readlane_b32 s24, v250, 8
	v_ashrrev_i32_e32 v39, 31, v38
	v_readlane_b32 s25, v250, 9
	v_readlane_b32 s26, v250, 10
	v_readlane_b32 s27, v250, 11
	v_lshl_add_u64 v[38:39], v[38:39], 2, s[24:25]
	global_load_dword v42, v[38:39], off nt
	global_load_dword v43, v[38:39], off offset:8 nt
	global_load_dword v74, v[38:39], off offset:16 nt
	global_load_dword v75, v[38:39], off offset:24 nt
	global_load_dword v76, v[38:39], off offset:32 nt
	global_load_dword v77, v[38:39], off offset:40 nt
	global_load_dword v78, v[38:39], off offset:48 nt
	global_load_dword v79, v[38:39], off offset:56 nt
	global_load_dword v80, v[38:39], off offset:64 nt
	global_load_dword v81, v[38:39], off offset:72 nt
	global_load_dword v82, v[38:39], off offset:80 nt
	global_load_dword v83, v[38:39], off offset:88 nt
	global_load_dword v84, v[38:39], off offset:96 nt
	global_load_dword v85, v[38:39], off offset:104 nt
	global_load_dword v86, v[38:39], off offset:112 nt
	global_load_dword v87, v[38:39], off offset:120 nt
	global_load_dword v88, v[38:39], off offset:128 nt
	global_load_dword v89, v[38:39], off offset:136 nt
	global_load_dword v90, v[38:39], off offset:144 nt
	global_load_dword v91, v[38:39], off offset:152 nt
	global_load_dword v92, v[38:39], off offset:160 nt
	global_load_dword v93, v[38:39], off offset:168 nt
	global_load_dword v94, v[38:39], off offset:176 nt
	global_load_dword v95, v[38:39], off offset:184 nt
	global_load_dword v96, v[38:39], off offset:192 nt
	global_load_dword v97, v[38:39], off offset:200 nt
	global_load_dword v98, v[38:39], off offset:208 nt
	global_load_dword v99, v[38:39], off offset:216 nt
	global_load_dword v100, v[38:39], off offset:224 nt
	global_load_dword v101, v[38:39], off offset:232 nt
	global_load_dword v102, v[38:39], off offset:240 nt
	global_load_dword v103, v[38:39], off offset:248 nt
	v_readlane_b32 s28, v250, 12
	v_readlane_b32 s29, v250, 13
	v_readlane_b32 s30, v250, 14
	v_readlane_b32 s31, v250, 15
	s_waitcnt vmcnt(30)
	v_pk_mul_f32 v[16:17], v[16:17], v[42:43]
	s_waitcnt vmcnt(28)
	v_pk_mul_f32 v[18:19], v[18:19], v[74:75]
	s_waitcnt vmcnt(26)
	v_pk_mul_f32 v[20:21], v[20:21], v[76:77]
	s_waitcnt vmcnt(24)
	v_pk_mul_f32 v[22:23], v[22:23], v[78:79]
	s_waitcnt vmcnt(22)
	v_pk_mul_f32 v[24:25], v[24:25], v[80:81]
	s_waitcnt vmcnt(20)
	v_pk_mul_f32 v[26:27], v[26:27], v[82:83]
	s_waitcnt vmcnt(18)
	v_pk_mul_f32 v[28:29], v[28:29], v[84:85]
	s_waitcnt vmcnt(16)
	v_pk_mul_f32 v[30:31], v[30:31], v[86:87]
	s_waitcnt vmcnt(14)
	v_pk_mul_f32 v[32:33], v[32:33], v[88:89]
	s_waitcnt vmcnt(12)
	v_pk_mul_f32 v[34:35], v[34:35], v[90:91]
	s_waitcnt vmcnt(10)
	v_pk_mul_f32 v[36:37], v[36:37], v[92:93]
	s_waitcnt vmcnt(8)
	v_pk_mul_f32 v[40:41], v[40:41], v[94:95]
	s_waitcnt vmcnt(6)
	v_pk_mul_f32 v[44:45], v[44:45], v[96:97]
	s_waitcnt vmcnt(4)
	v_pk_mul_f32 v[46:47], v[46:47], v[98:99]
	s_waitcnt vmcnt(2)
	v_pk_mul_f32 v[48:49], v[48:49], v[100:101]
	s_waitcnt vmcnt(0)
	v_pk_mul_f32 v[50:51], v[50:51], v[102:103]

; __device__ __forceinline__ int orig_wgu(int np) { const int T = np >> 8, cl = np & 255; return ((cl >> 7) ? DFF : 0) + 128 * T + (cl & 127); }
; template <int MODE> __device__ __forceinline__ void wt_item(const float* W, int K, int N, int Np, const float* gain, bf16_t* WT, int item, float* scr, int lane) {
;     const int nblk = Np / 32, kb = item / nblk, nb = item - kb * nblk, k0 = 64 * kb, n0 = 32 * nb;
;     const int np = n0 + (lane & 31); const int o = (MODE == 1) ? orig_win(np) : (MODE == 2) ? orig_wgu(np) : np;
;     float wv[32];
; #pragma unroll
;     for (int i = 0; i < 32; ++i) { const int kk = 2 * i + (lane >> 5); wv[i] = (o >= 0) ? W[(size_t)(k0 + kk) * N + o] : 0.f; }
; __device__ __forceinline__ void ph0_prologue(const Ctx& C, unsigned char* lds) {
;     ...
;         if (r < I_O) { wt_item<0>(C.w_o, DM, DM, DM, nullptr, (bf16_t*)(C.ws + WS_WO), r, scr, C.lane); continue; } r -= I_O;
.LBB0_88:
	s_andn2_b64 vcc, exec, s[6:7]
	s_cbranch_vccnz .LBB0_90
	s_lshl_b32 s6, s20, 1
	s_and_b32 s6, s6, 0x3fc0
	s_add_i32 s8, s6, 0xffffe100
	s_lshl_b32 s6, s20, 5
	s_and_b32 s6, s6, 0x3e0
	v_or_b32_e32 v0, s6, v67
	v_add_u32_e32 v16, s8, v52
	v_readlane_b32 s52, v250, 39
	v_lshlrev_b32_e32 v0, 2, v0
	v_readlane_b32 s66, v250, 53
	v_readlane_b32 s67, v250, 54
	v_ashrrev_i32_e32 v17, 31, v16
	v_lshlrev_b64 v[16:17], 12, v[16:17]
	v_lshl_add_u64 v[18:19], s[66:67], 0, v[0:1]
	v_lshl_add_u64 v[16:17], v[18:19], 0, v[16:17]
	v_add_co_u32_e32 v18, vcc, 0x2000, v16
	v_readlane_b32 s53, v250, 40
	s_nop 0
	v_addc_co_u32_e32 v19, vcc, 0, v17, vcc
	v_add_co_u32_e32 v20, vcc, 0x4000, v16
	v_readlane_b32 s54, v250, 41
	s_nop 0
	v_addc_co_u32_e32 v21, vcc, 0, v17, vcc
	v_add_co_u32_e32 v22, vcc, 0x6000, v16
	v_readlane_b32 s55, v250, 42
	s_nop 0
	v_addc_co_u32_e32 v23, vcc, 0, v17, vcc
	v_add_co_u32_e32 v24, vcc, 0x8000, v16
	v_readlane_b32 s56, v250, 43
	s_nop 0
	v_addc_co_u32_e32 v25, vcc, 0, v17, vcc
	v_add_co_u32_e32 v26, vcc, 0xa000, v16
	v_readlane_b32 s57, v250, 44
	s_nop 0
	v_addc_co_u32_e32 v27, vcc, 0, v17, vcc
	v_add_co_u32_e32 v28, vcc, 0xc000, v16
	v_readlane_b32 s58, v250, 45
	s_nop 0
	v_addc_co_u32_e32 v29, vcc, 0, v17, vcc
	v_add_co_u32_e32 v30, vcc, 0xe000, v16
	v_readlane_b32 s59, v250, 46
	s_nop 0
	v_addc_co_u32_e32 v31, vcc, 0, v17, vcc
	global_load_dword v0, v[16:17], off nt
	global_load_dword v34, v[18:19], off nt
	global_load_dword v35, v[20:21], off nt
	global_load_dword v36, v[22:23], off nt
	global_load_dword v37, v[24:25], off nt
	global_load_dword v38, v[26:27], off nt
	global_load_dword v39, v[28:29], off nt
	global_load_dword v40, v[30:31], off nt
	v_add_co_u32_e32 v18, vcc, 0x10000, v16
	v_readlane_b32 s60, v250, 47
	s_nop 0
	v_addc_co_u32_e32 v19, vcc, 0, v17, vcc
	v_add_co_u32_e32 v20, vcc, 0x12000, v16
	v_readlane_b32 s61, v250, 48
	s_nop 0
	v_addc_co_u32_e32 v21, vcc, 0, v17, vcc
	v_add_co_u32_e32 v22, vcc, 0x14000, v16
	v_readlane_b32 s62, v250, 49
	s_nop 0
	v_addc_co_u32_e32 v23, vcc, 0, v17, vcc
	v_add_co_u32_e32 v24, vcc, 0x16000, v16
	v_readlane_b32 s63, v250, 50
	s_nop 0
	v_addc_co_u32_e32 v25, vcc, 0, v17, vcc
	v_add_co_u32_e32 v26, vcc, 0x18000, v16
	v_readlane_b32 s64, v250, 51
	s_nop 0
	v_addc_co_u32_e32 v27, vcc, 0, v17, vcc
	v_add_co_u32_e32 v28, vcc, 0x1a000, v16
	v_readlane_b32 s65, v250, 52
	s_nop 0
	v_addc_co_u32_e32 v29, vcc, 0, v17, vcc
	v_add_co_u32_e32 v30, vcc, 0x1c000, v16
	s_nop 1
	v_addc_co_u32_e32 v31, vcc, 0, v17, vcc
	v_add_co_u32_e32 v32, vcc, 0x1e000, v16
	s_nop 1
	v_addc_co_u32_e32 v33, vcc, 0, v17, vcc
	global_load_dword v41, v[18:19], off nt
	global_load_dword v42, v[20:21], off nt
	global_load_dword v43, v[22:23], off nt
	global_load_dword v44, v[24:25], off nt
	global_load_dword v45, v[26:27], off nt
	global_load_dword v46, v[28:29], off nt
	global_load_dword v47, v[30:31], off nt
	global_load_dword v48, v[32:33], off nt
	v_add_co_u32_e32 v18, vcc, 0x20000, v16
	s_nop 1
	v_addc_co_u32_e32 v19, vcc, 0, v17, vcc
	v_add_co_u32_e32 v20, vcc, 0x22000, v16
	s_nop 1
	v_addc_co_u32_e32 v21, vcc, 0, v17, vcc
	v_add_co_u32_e32 v22, vcc, 0x24000, v16
	s_nop 1
	v_addc_co_u32_e32 v23, vcc, 0, v17, vcc
	v_add_co_u32_e32 v24, vcc, 0x26000, v16
	s_nop 1
	v_addc_co_u32_e32 v25, vcc, 0, v17, vcc
	v_add_co_u32_e32 v26, vcc, 0x28000, v16
	s_nop 1
	v_addc_co_u32_e32 v27, vcc, 0, v17, vcc
	v_add_co_u32_e32 v28, vcc, 0x2a000, v16
	s_nop 1
	v_addc_co_u32_e32 v29, vcc, 0, v17, vcc
	v_add_co_u32_e32 v30, vcc, 0x2c000, v16
	s_nop 1
	v_addc_co_u32_e32 v31, vcc, 0, v17, vcc
	v_add_co_u32_e32 v32, vcc, 0x2e000, v16
	s_nop 1
	v_addc_co_u32_e32 v33, vcc, 0, v17, vcc
	global_load_dword v49, v[18:19], off nt
	global_load_dword v50, v[20:21], off nt
	global_load_dword v51, v[22:23], off nt
	global_load_dword v74, v[24:25], off nt
	global_load_dword v75, v[26:27], off nt
	global_load_dword v76, v[28:29], off nt
	global_load_dword v77, v[30:31], off nt
	s_nop 0
	global_load_dword v32, v[32:33], off nt
	v_add_co_u32_e32 v18, vcc, 0x30000, v16
	s_nop 1
	v_addc_co_u32_e32 v19, vcc, 0, v17, vcc
	v_add_co_u32_e32 v20, vcc, 0x32000, v16
	s_nop 1
	v_addc_co_u32_e32 v21, vcc, 0, v17, vcc
	v_add_co_u32_e32 v22, vcc, 0x34000, v16
	s_nop 1
	v_addc_co_u32_e32 v23, vcc, 0, v17, vcc
	v_add_co_u32_e32 v24, vcc, 0x36000, v16
	s_nop 1
	v_addc_co_u32_e32 v25, vcc, 0, v17, vcc
	v_add_co_u32_e32 v26, vcc, 0x38000, v16
	s_nop 1
	v_addc_co_u32_e32 v27, vcc, 0, v17, vcc
	v_add_co_u32_e32 v28, vcc, 0x3a000, v16
	s_nop 1
	v_addc_co_u32_e32 v29, vcc, 0, v17, vcc
	v_add_co_u32_e32 v30, vcc, 0x3c000, v16
	s_nop 1
	v_addc_co_u32_e32 v31, vcc, 0, v17, vcc
	v_add_co_u32_e32 v16, vcc, 0x3e000, v16
	s_nop 1
	v_addc_co_u32_e32 v17, vcc, 0, v17, vcc
	global_load_dword v18, v[18:19], off nt
	s_nop 0
	global_load_dword v19, v[20:21], off nt
	s_nop 0
	global_load_dword v20, v[22:23], off nt
	global_load_dword v21, v[24:25], off nt
	s_nop 0
	global_load_dword v22, v[26:27], off nt
	global_load_dword v23, v[28:29], off nt
	global_load_dword v24, v[30:31], off nt
	s_nop 0
	global_load_dword v16, v[16:17], off nt
	s_waitcnt vmcnt(30)
; __device__ __forceinline__ unsigned cvt_pk_bf16(float lo, float hi) { unsigned r; asm volatile("v_cvt_pk_bf16_f32 %0, %1, %2" : "=v"(r) : "v"(lo), "v"(hi)); return r; }
; #define LDS_WAIT() asm volatile("s_waitcnt lgkmcnt(0)" ::: "memory")
; template <int MODE> __device__ __forceinline__ void wt_item(const float* W, int K, int N, int Np, const float* gain, bf16_t* WT, int item, float* scr, int lane) {
;     ...
;     for (int i = 0; i < 32; ++i) scr[(2 * i + (lane >> 5)) * 33 + (lane & 31)] = wv[i];
;     LDS_WAIT();
;     const int c = lane & 7;
; #pragma unroll
;     for (int j = 0; j < 4; ++j) { const int n = (lane >> 3) + 8 * j; const float* s = scr + (8 * c) * 33 + n;
;         u32x4 ov; ov.x = cvt_pk_bf16(s[0 * 33], s[1 * 33]); ov.y = cvt_pk_bf16(s[2 * 33], s[3 * 33]); ov.z = cvt_pk_bf16(s[4 * 33], s[5 * 33]); ov.w = cvt_pk_bf16(s[6 * 33], s[7 * 33]);
;         *(u32x4*)(WT + (size_t)(n0 + n) * K + k0 + 8 * c) = ov; }
;     LDS_WAIT();
	ds_write2_b32 v53, v0, v34 offset1:66
	s_waitcnt vmcnt(28)
	ds_write2_b32 v53, v35, v36 offset0:132 offset1:198
	s_waitcnt vmcnt(26)
	ds_write2_b32 v61, v37, v38 offset0:8 offset1:74
	s_waitcnt vmcnt(24)
	ds_write2_b32 v61, v39, v40 offset0:140 offset1:206
	s_waitcnt vmcnt(22)
	ds_write2_b32 v62, v41, v42 offset0:16 offset1:82
	s_waitcnt vmcnt(20)
	ds_write2_b32 v62, v43, v44 offset0:148 offset1:214
	s_waitcnt vmcnt(18)
	ds_write2_b32 v63, v45, v46 offset0:24 offset1:90
	s_waitcnt vmcnt(16)
	ds_write2_b32 v63, v47, v48 offset0:156 offset1:222
	s_waitcnt vmcnt(14)
	ds_write2_b32 v65, v49, v50 offset0:32 offset1:98
	s_waitcnt vmcnt(12)
	ds_write2_b32 v65, v51, v74 offset0:164 offset1:230
	s_waitcnt vmcnt(10)
	ds_write2_b32 v68, v75, v76 offset0:40 offset1:106
	s_waitcnt vmcnt(8)
	ds_write2_b32 v68, v77, v32 offset0:172 offset1:238
	s_waitcnt vmcnt(6)
	ds_write2_b32 v69, v18, v19 offset0:48 offset1:114
	s_waitcnt vmcnt(4)
	ds_write2_b32 v69, v20, v21 offset0:180 offset1:246
	s_waitcnt vmcnt(2)
	ds_write2_b32 v70, v22, v23 offset0:56 offset1:122
	s_waitcnt vmcnt(0)
	ds_write2_b32 v70, v24, v16 offset0:188 offset1:254
	s_waitcnt lgkmcnt(0)
	ds_read2_b32 v[16:17], v55 offset1:33
	s_waitcnt lgkmcnt(0)
	v_cvt_pk_bf16_f32 v16, v16, v17
	ds_read2_b32 v[18:19], v55 offset0:66 offset1:99
	s_waitcnt lgkmcnt(0)
	v_cvt_pk_bf16_f32 v17, v18, v19
	ds_read2_b32 v[18:19], v55 offset0:132 offset1:165
	s_waitcnt lgkmcnt(0)
	v_cvt_pk_bf16_f32 v18, v18, v19
	ds_read2_b32 v[20:21], v55 offset0:198 offset1:231
	s_waitcnt lgkmcnt(0)
	v_cvt_pk_bf16_f32 v19, v20, v21
	v_add_u32_e32 v20, s6, v54
	v_ashrrev_i32_e32 v21, 31, v20
	v_lshl_add_u64 v[22:23], s[8:9], 1, v[6:7]
	v_lshlrev_b64 v[20:21], 11, v[20:21]
	v_lshl_add_u64 v[20:21], v[22:23], 0, v[20:21]
	ds_read2_b32 v[24:25], v55 offset0:8 offset1:41
	global_store_dwordx4 v[20:21], v[16:19], off
	s_waitcnt lgkmcnt(0)
	s_nop 0
	v_cvt_pk_bf16_f32 v16, v24, v25
	ds_read2_b32 v[18:19], v55 offset0:74 offset1:107
	s_waitcnt lgkmcnt(0)
	v_cvt_pk_bf16_f32 v17, v18, v19
	ds_read2_b32 v[18:19], v55 offset0:140 offset1:173
	s_waitcnt lgkmcnt(0)
	v_cvt_pk_bf16_f32 v18, v18, v19
	ds_read2_b32 v[20:21], v55 offset0:206 offset1:239
	s_waitcnt lgkmcnt(0)
	v_cvt_pk_bf16_f32 v19, v20, v21
	v_add_u32_e32 v20, s6, v56
	v_ashrrev_i32_e32 v21, 31, v20
	v_lshlrev_b64 v[20:21], 11, v[20:21]
	v_lshl_add_u64 v[20:21], v[22:23], 0, v[20:21]
	ds_read2_b32 v[24:25], v55 offset0:16 offset1:49
	global_store_dwordx4 v[20:21], v[16:19], off
	s_waitcnt lgkmcnt(0)
	s_nop 0
	v_cvt_pk_bf16_f32 v16, v24, v25
	ds_read2_b32 v[18:19], v55 offset0:82 offset1:115
	s_waitcnt lgkmcnt(0)
	v_cvt_pk_bf16_f32 v17, v18, v19
	ds_read2_b32 v[18:19], v55 offset0:148 offset1:181
	s_waitcnt lgkmcnt(0)
	v_cvt_pk_bf16_f32 v18, v18, v19
	ds_read2_b32 v[20:21], v55 offset0:214 offset1:247
	s_waitcnt lgkmcnt(0)
	v_cvt_pk_bf16_f32 v19, v20, v21
	v_add_u32_e32 v20, s6, v57
	v_ashrrev_i32_e32 v21, 31, v20
	v_lshlrev_b64 v[20:21], 11, v[20:21]
	v_lshl_add_u64 v[20:21], v[22:23], 0, v[20:21]
	ds_read2_b32 v[24:25], v55 offset0:24 offset1:57
	global_store_dwordx4 v[20:21], v[16:19], off
	s_waitcnt lgkmcnt(0)
	s_nop 0
	v_cvt_pk_bf16_f32 v16, v24, v25
	ds_read2_b32 v[18:19], v55 offset0:90 offset1:123
	s_waitcnt lgkmcnt(0)
	v_cvt_pk_bf16_f32 v17, v18, v19
	ds_read2_b32 v[18:19], v55 offset0:156 offset1:189
	s_waitcnt lgkmcnt(0)
	v_cvt_pk_bf16_f32 v18, v18, v19
	ds_read2_b32 v[20:21], v55 offset0:222 offset1:255
	s_waitcnt lgkmcnt(0)
	v_cvt_pk_bf16_f32 v19, v20, v21
	v_add_u32_e32 v20, s6, v58
	v_ashrrev_i32_e32 v21, 31, v20
	v_lshlrev_b64 v[20:21], 11, v[20:21]
	v_lshl_add_u64 v[20:21], v[22:23], 0, v[20:21]
	global_store_dwordx4 v[20:21], v[16:19], off
	s_waitcnt lgkmcnt(0)

; __device__ __forceinline__ int orig_wgu(int np) { const int T = np >> 8, cl = np & 255; return ((cl >> 7) ? DFF : 0) + 128 * T + (cl & 127); }
; template <int MODE> __device__ __forceinline__ void wt_item(const float* W, int K, int N, int Np, const float* gain, bf16_t* WT, int item, float* scr, int lane) {
;     const int nblk = Np / 32, kb = item / nblk, nb = item - kb * nblk, k0 = 64 * kb, n0 = 32 * nb;
;     const int np = n0 + (lane & 31); const int o = (MODE == 1) ? orig_win(np) : (MODE == 2) ? orig_wgu(np) : np;
;     float wv[32];
; #pragma unroll
;     for (int i = 0; i < 32; ++i) { const int kk = 2 * i + (lane >> 5); wv[i] = (o >= 0) ? W[(size_t)(k0 + kk) * N + o] : 0.f; }
; __device__ __forceinline__ void ph0_prologue(const Ctx& C, unsigned char* lds) {
;     ...
;         if (r < I_KV) { wt_item<0>(C.w_kv, DM, 2 * DM, 2 * DM, C.g_mem_src, (bf16_t*)(C.ws + WS_WKV), r, scr, C.lane); continue; } r -= I_KV;
.LBB0_91:
	s_andn2_b64 vcc, exec, s[6:7]
	s_cbranch_vccnz .LBB0_95
	s_and_b32 s6, s20, 0xfc0
	s_add_i32 s8, s6, 0xfffff480
	s_lshl_b32 s6, s20, 5
	s_and_b32 s6, s6, 0x7e0
	v_or_b32_e32 v0, s6, v67
	v_add_u32_e32 v40, s8, v52
	v_readlane_b32 s52, v250, 39
	v_lshlrev_b32_e32 v0, 2, v0
	v_readlane_b32 s60, v250, 47
	v_readlane_b32 s61, v250, 48
	v_ashrrev_i32_e32 v41, 31, v40
	v_lshlrev_b64 v[18:19], 13, v[40:41]
	v_lshl_add_u64 v[16:17], s[60:61], 0, v[0:1]
	v_lshl_add_u64 v[42:43], v[16:17], 0, v[18:19]
	v_add_co_u32_e32 v18, vcc, 0x4000, v42
	v_readlane_b32 s56, v250, 43
	s_nop 0
	v_addc_co_u32_e32 v19, vcc, 0, v43, vcc
	v_add_co_u32_e32 v20, vcc, 0x8000, v42
	v_readlane_b32 s57, v250, 44
	s_nop 0
	v_addc_co_u32_e32 v21, vcc, 0, v43, vcc
	v_add_co_u32_e32 v22, vcc, 0xc000, v42
	v_readlane_b32 s53, v250, 40
	s_nop 0
	v_addc_co_u32_e32 v23, vcc, 0, v43, vcc
	v_add_co_u32_e32 v24, vcc, 0x10000, v42
	v_readlane_b32 s54, v250, 41
	s_nop 0
	v_addc_co_u32_e32 v25, vcc, 0, v43, vcc
	v_add_co_u32_e32 v26, vcc, 0x14000, v42
	v_readlane_b32 s55, v250, 42
	s_nop 0
	v_addc_co_u32_e32 v27, vcc, 0, v43, vcc
	v_add_co_u32_e32 v28, vcc, 0x18000, v42
	v_readlane_b32 s58, v250, 45
	s_nop 0
	v_addc_co_u32_e32 v29, vcc, 0, v43, vcc
	v_add_co_u32_e32 v30, vcc, 0x1c000, v42
	v_readlane_b32 s59, v250, 46
	s_nop 0
	v_addc_co_u32_e32 v31, vcc, 0, v43, vcc
	global_load_dword v16, v[42:43], off nt
	global_load_dword v17, v[18:19], off nt
	s_nop 0
	global_load_dword v18, v[20:21], off nt
	global_load_dword v19, v[22:23], off nt
	s_nop 0
	global_load_dword v20, v[24:25], off nt
	global_load_dword v21, v[26:27], off nt
	global_load_dword v22, v[28:29], off nt
	global_load_dword v23, v[30:31], off nt
	v_add_co_u32_e32 v24, vcc, 0x20000, v42
	v_readlane_b32 s62, v250, 49
	s_nop 0
	v_addc_co_u32_e32 v25, vcc, 0, v43, vcc
	v_add_co_u32_e32 v26, vcc, 0x24000, v42
	v_readlane_b32 s63, v250, 50
	s_nop 0
	v_addc_co_u32_e32 v27, vcc, 0, v43, vcc
	v_add_co_u32_e32 v28, vcc, 0x28000, v42
	v_readlane_b32 s64, v250, 51
	s_nop 0
	v_addc_co_u32_e32 v29, vcc, 0, v43, vcc
	v_add_co_u32_e32 v30, vcc, 0x2c000, v42
	v_readlane_b32 s65, v250, 52
	s_nop 0
	v_addc_co_u32_e32 v31, vcc, 0, v43, vcc
	v_add_co_u32_e32 v32, vcc, 0x30000, v42
	v_readlane_b32 s66, v250, 53
	s_nop 0
	v_addc_co_u32_e32 v33, vcc, 0, v43, vcc
	v_add_co_u32_e32 v34, vcc, 0x34000, v42
	v_readlane_b32 s67, v250, 54
	s_nop 0
	v_addc_co_u32_e32 v35, vcc, 0, v43, vcc
	v_add_co_u32_e32 v36, vcc, 0x38000, v42
	s_nop 1
	v_addc_co_u32_e32 v37, vcc, 0, v43, vcc
	v_add_co_u32_e32 v38, vcc, 0x3c000, v42
	s_nop 1
	v_addc_co_u32_e32 v39, vcc, 0, v43, vcc
	global_load_dword v24, v[24:25], off nt
	s_nop 0
	global_load_dword v25, v[26:27], off nt
	s_nop 0
	global_load_dword v26, v[28:29], off nt
	global_load_dword v27, v[30:31], off nt
	s_nop 0
	global_load_dword v28, v[32:33], off nt
	global_load_dword v29, v[34:35], off nt
	global_load_dword v30, v[36:37], off nt
	global_load_dword v31, v[38:39], off nt
	v_add_co_u32_e32 v32, vcc, 0x40000, v42
	s_nop 1
	v_addc_co_u32_e32 v33, vcc, 0, v43, vcc
	v_add_co_u32_e32 v34, vcc, 0x44000, v42
	s_nop 1
	v_addc_co_u32_e32 v35, vcc, 0, v43, vcc
	v_add_co_u32_e32 v36, vcc, 0x48000, v42
	s_nop 1
	v_addc_co_u32_e32 v37, vcc, 0, v43, vcc
	v_add_co_u32_e32 v38, vcc, 0x4c000, v42
	s_nop 1
	v_addc_co_u32_e32 v39, vcc, 0, v43, vcc
	v_add_co_u32_e32 v44, vcc, 0x50000, v42
	s_nop 1
	v_addc_co_u32_e32 v45, vcc, 0, v43, vcc
	v_add_co_u32_e32 v46, vcc, 0x54000, v42
	s_nop 1
	v_addc_co_u32_e32 v47, vcc, 0, v43, vcc
	v_add_co_u32_e32 v48, vcc, 0x58000, v42
	s_nop 1
	v_addc_co_u32_e32 v49, vcc, 0, v43, vcc
	v_add_co_u32_e32 v50, vcc, 0x5c000, v42
	s_nop 1
	v_addc_co_u32_e32 v51, vcc, 0, v43, vcc
	global_load_dword v32, v[32:33], off nt
	s_nop 0
	global_load_dword v33, v[34:35], off nt
	s_nop 0
	global_load_dword v34, v[36:37], off nt
	global_load_dword v35, v[38:39], off nt
	s_nop 0
	global_load_dword v36, v[44:45], off nt
	global_load_dword v37, v[46:47], off nt
	global_load_dword v38, v[48:49], off nt
	global_load_dword v39, v[50:51], off nt
	v_add_co_u32_e32 v44, vcc, 0x60000, v42
	s_nop 1
	v_addc_co_u32_e32 v45, vcc, 0, v43, vcc
	v_add_co_u32_e32 v46, vcc, 0x64000, v42
	s_nop 1
	v_addc_co_u32_e32 v47, vcc, 0, v43, vcc
	v_add_co_u32_e32 v48, vcc, 0x68000, v42
	s_nop 1
	v_addc_co_u32_e32 v49, vcc, 0, v43, vcc
	v_add_co_u32_e32 v50, vcc, 0x6c000, v42
	s_nop 1
	v_addc_co_u32_e32 v51, vcc, 0, v43, vcc
	v_add_co_u32_e32 v74, vcc, 0x70000, v42
	s_nop 1
	v_addc_co_u32_e32 v75, vcc, 0, v43, vcc
	v_add_co_u32_e32 v76, vcc, 0x74000, v42
	s_nop 1
	v_addc_co_u32_e32 v77, vcc, 0, v43, vcc
	v_add_co_u32_e32 v78, vcc, 0x78000, v42
	s_nop 1
	v_addc_co_u32_e32 v79, vcc, 0, v43, vcc
	v_add_co_u32_e32 v80, vcc, 0x7c000, v42
	s_nop 1
	v_addc_co_u32_e32 v81, vcc, 0, v43, vcc
	global_load_dword v42, v[44:45], off nt
	global_load_dword v43, v[46:47], off nt
	s_nop 0
	global_load_dword v44, v[48:49], off nt
	global_load_dword v45, v[50:51], off nt
	s_nop 0
	global_load_dword v48, v[74:75], off nt
	global_load_dword v49, v[76:77], off nt
	global_load_dword v46, v[78:79], off nt
	global_load_dword v47, v[80:81], off nt
	s_andn2_b64 vcc, exec, s[12:13]
	s_cbranch_vccnz .LBB0_94
; template <int MODE> __device__ __forceinline__ void wt_item(const float* W, int K, int N, int Np, const float* gain, bf16_t* WT, int item, float* scr, int lane) {
;     ...
;     if (gain) {
;         float gv[32];
; #pragma unroll
;         for (int i = 0; i < 32; ++i) gv[i] = gain[k0 + 2 * i + (lane >> 5)];
; #pragma unroll
;         for (int i = 0; i < 32; ++i) wv[i] *= gv[i];
	v_lshl_add_u64 v[40:41], v[40:41], 2, s[56:57]
	global_load_dword v50, v[40:41], off nt
	global_load_dword v51, v[40:41], off offset:8 nt
	global_load_dword v74, v[40:41], off offset:16 nt
	global_load_dword v75, v[40:41], off offset:24 nt
	global_load_dword v76, v[40:41], off offset:32 nt
	global_load_dword v77, v[40:41], off offset:40 nt
	global_load_dword v78, v[40:41], off offset:48 nt
	global_load_dword v79, v[40:41], off offset:56 nt
	global_load_dword v80, v[40:41], off offset:64 nt
	global_load_dword v81, v[40:41], off offset:72 nt
	global_load_dword v82, v[40:41], off offset:80 nt
	global_load_dword v83, v[40:41], off offset:88 nt
	global_load_dword v84, v[40:41], off offset:96 nt
	global_load_dword v85, v[40:41], off offset:104 nt
	global_load_dword v86, v[40:41], off offset:112 nt
	global_load_dword v87, v[40:41], off offset:120 nt
	global_load_dword v88, v[40:41], off offset:128 nt
	global_load_dword v89, v[40:41], off offset:136 nt
	global_load_dword v90, v[40:41], off offset:144 nt
	global_load_dword v91, v[40:41], off offset:152 nt
	global_load_dword v92, v[40:41], off offset:160 nt
	global_load_dword v93, v[40:41], off offset:168 nt
	global_load_dword v94, v[40:41], off offset:176 nt
	global_load_dword v95, v[40:41], off offset:184 nt
	global_load_dword v96, v[40:41], off offset:192 nt
	global_load_dword v97, v[40:41], off offset:200 nt
	global_load_dword v98, v[40:41], off offset:208 nt
	global_load_dword v99, v[40:41], off offset:216 nt
	global_load_dword v100, v[40:41], off offset:224 nt
	global_load_dword v101, v[40:41], off offset:232 nt
	global_load_dword v102, v[40:41], off offset:240 nt
	global_load_dword v103, v[40:41], off offset:248 nt
	s_waitcnt vmcnt(30)
	v_pk_mul_f32 v[16:17], v[16:17], v[50:51]
	s_waitcnt vmcnt(28)
	v_pk_mul_f32 v[18:19], v[18:19], v[74:75]
	s_waitcnt vmcnt(26)
	v_pk_mul_f32 v[20:21], v[20:21], v[76:77]
	s_waitcnt vmcnt(24)
	v_pk_mul_f32 v[22:23], v[22:23], v[78:79]
	s_waitcnt vmcnt(22)
	v_pk_mul_f32 v[24:25], v[24:25], v[80:81]
	s_waitcnt vmcnt(20)
	v_pk_mul_f32 v[26:27], v[26:27], v[82:83]
	s_waitcnt vmcnt(18)
	v_pk_mul_f32 v[28:29], v[28:29], v[84:85]
	s_waitcnt vmcnt(16)
	v_pk_mul_f32 v[30:31], v[30:31], v[86:87]
	s_waitcnt vmcnt(14)
	v_pk_mul_f32 v[32:33], v[32:33], v[88:89]
	s_waitcnt vmcnt(12)
	v_pk_mul_f32 v[34:35], v[34:35], v[90:91]
	s_waitcnt vmcnt(10)
	v_pk_mul_f32 v[36:37], v[36:37], v[92:93]
	s_waitcnt vmcnt(8)
	v_pk_mul_f32 v[38:39], v[38:39], v[94:95]
	s_waitcnt vmcnt(6)
	v_pk_mul_f32 v[42:43], v[42:43], v[96:97]
	s_waitcnt vmcnt(4)
	v_pk_mul_f32 v[44:45], v[44:45], v[98:99]
	s_waitcnt vmcnt(2)
	v_pk_mul_f32 v[48:49], v[48:49], v[100:101]
	s_waitcnt vmcnt(0)
	v_pk_mul_f32 v[46:47], v[46:47], v[102:103]

; __device__ __forceinline__ int orig_wgu(int np) { const int T = np >> 8, cl = np & 255; return ((cl >> 7) ? DFF : 0) + 128 * T + (cl & 127); }
; template <int MODE> __device__ __forceinline__ void wt_item(const float* W, int K, int N, int Np, const float* gain, bf16_t* WT, int item, float* scr, int lane) {
;     const int nblk = Np / 32, kb = item / nblk, nb = item - kb * nblk, k0 = 64 * kb, n0 = 32 * nb;
;     const int np = n0 + (lane & 31); const int o = (MODE == 1) ? orig_win(np) : (MODE == 2) ? orig_wgu(np) : np;
;     float wv[32];
; #pragma unroll
;     for (int i = 0; i < 32; ++i) { const int kk = 2 * i + (lane >> 5); wv[i] = (o >= 0) ? W[(size_t)(k0 + kk) * N + o] : 0.f; }
; __device__ __forceinline__ void ph0_prologue(const Ctx& C, unsigned char* lds) {
;     ...
;         if (r < I_Q) { wt_item<0>(C.w_q, DM, DM, DM, C.g_mem, (bf16_t*)(C.ws + WS_WQ), r, scr, C.lane); continue; } r -= I_Q;
.LBB0_96:
	s_andn2_b64 vcc, exec, s[6:7]
	s_cbranch_vccnz .LBB0_100
	s_lshl_b32 s6, s20, 1
	s_and_b32 s6, s6, 0x1fc0
	s_add_i32 s8, s6, 0xffffed00
	s_lshl_b32 s6, s20, 5
	s_and_b32 s6, s6, 0x3e0
	v_or_b32_e32 v0, s6, v67
	v_add_u32_e32 v40, s8, v52
	v_readlane_b32 s52, v250, 39
	v_lshlrev_b32_e32 v0, 2, v0
	v_readlane_b32 s58, v250, 45
	v_readlane_b32 s59, v250, 46
	v_ashrrev_i32_e32 v41, 31, v40
	v_lshlrev_b64 v[18:19], 12, v[40:41]
	v_lshl_add_u64 v[16:17], s[58:59], 0, v[0:1]
	v_lshl_add_u64 v[42:43], v[16:17], 0, v[18:19]
	v_add_co_u32_e32 v18, vcc, 0x2000, v42
	v_readlane_b32 s54, v250, 41
	s_nop 0
	v_addc_co_u32_e32 v19, vcc, 0, v43, vcc
	v_add_co_u32_e32 v20, vcc, 0x4000, v42
	v_readlane_b32 s55, v250, 42
	s_nop 0
	v_addc_co_u32_e32 v21, vcc, 0, v43, vcc
	v_add_co_u32_e32 v22, vcc, 0x6000, v42
	v_readlane_b32 s53, v250, 40
	s_nop 0
	v_addc_co_u32_e32 v23, vcc, 0, v43, vcc
	v_add_co_u32_e32 v24, vcc, 0x8000, v42
	v_readlane_b32 s56, v250, 43
	s_nop 0
	v_addc_co_u32_e32 v25, vcc, 0, v43, vcc
	v_add_co_u32_e32 v26, vcc, 0xa000, v42
	v_readlane_b32 s57, v250, 44
	s_nop 0
	v_addc_co_u32_e32 v27, vcc, 0, v43, vcc
	v_add_co_u32_e32 v28, vcc, 0xc000, v42
	v_readlane_b32 s60, v250, 47
	s_nop 0
	v_addc_co_u32_e32 v29, vcc, 0, v43, vcc
	v_add_co_u32_e32 v30, vcc, 0xe000, v42
	v_readlane_b32 s61, v250, 48
	s_nop 0
	v_addc_co_u32_e32 v31, vcc, 0, v43, vcc
	global_load_dword v16, v[42:43], off nt
	global_load_dword v17, v[18:19], off nt
	s_nop 0
	global_load_dword v18, v[20:21], off nt
	global_load_dword v19, v[22:23], off nt
	s_nop 0
	global_load_dword v20, v[24:25], off nt
	global_load_dword v21, v[26:27], off nt
	global_load_dword v22, v[28:29], off nt
	global_load_dword v23, v[30:31], off nt
	v_add_co_u32_e32 v24, vcc, 0x10000, v42
	v_readlane_b32 s62, v250, 49
	s_nop 0
	v_addc_co_u32_e32 v25, vcc, 0, v43, vcc
	v_add_co_u32_e32 v26, vcc, 0x12000, v42
	v_readlane_b32 s63, v250, 50
	s_nop 0
	v_addc_co_u32_e32 v27, vcc, 0, v43, vcc
	v_add_co_u32_e32 v28, vcc, 0x14000, v42
	v_readlane_b32 s64, v250, 51
	s_nop 0
	v_addc_co_u32_e32 v29, vcc, 0, v43, vcc
	v_add_co_u32_e32 v30, vcc, 0x16000, v42
	v_readlane_b32 s65, v250, 52
	s_nop 0
	v_addc_co_u32_e32 v31, vcc, 0, v43, vcc
	v_add_co_u32_e32 v32, vcc, 0x18000, v42
	v_readlane_b32 s66, v250, 53
	s_nop 0
	v_addc_co_u32_e32 v33, vcc, 0, v43, vcc
	v_add_co_u32_e32 v34, vcc, 0x1a000, v42
	v_readlane_b32 s67, v250, 54
	s_nop 0
	v_addc_co_u32_e32 v35, vcc, 0, v43, vcc
	v_add_co_u32_e32 v36, vcc, 0x1c000, v42
	s_nop 1
	v_addc_co_u32_e32 v37, vcc, 0, v43, vcc
	v_add_co_u32_e32 v38, vcc, 0x1e000, v42
	s_nop 1
	v_addc_co_u32_e32 v39, vcc, 0, v43, vcc
	global_load_dword v24, v[24:25], off nt
	s_nop 0
	global_load_dword v25, v[26:27], off nt
	s_nop 0
	global_load_dword v26, v[28:29], off nt
	global_load_dword v27, v[30:31], off nt
	s_nop 0
	global_load_dword v28, v[32:33], off nt
	global_load_dword v29, v[34:35], off nt
	global_load_dword v30, v[36:37], off nt
	global_load_dword v31, v[38:39], off nt
	v_add_co_u32_e32 v32, vcc, 0x20000, v42
	s_nop 1
	v_addc_co_u32_e32 v33, vcc, 0, v43, vcc
	v_add_co_u32_e32 v34, vcc, 0x22000, v42
	s_nop 1
	v_addc_co_u32_e32 v35, vcc, 0, v43, vcc
	v_add_co_u32_e32 v36, vcc, 0x24000, v42
	s_nop 1
	v_addc_co_u32_e32 v37, vcc, 0, v43, vcc
	v_add_co_u32_e32 v38, vcc, 0x26000, v42
	s_nop 1
	v_addc_co_u32_e32 v39, vcc, 0, v43, vcc
	v_add_co_u32_e32 v44, vcc, 0x28000, v42
	s_nop 1
	v_addc_co_u32_e32 v45, vcc, 0, v43, vcc
	v_add_co_u32_e32 v46, vcc, 0x2a000, v42
	s_nop 1
	v_addc_co_u32_e32 v47, vcc, 0, v43, vcc
	v_add_co_u32_e32 v48, vcc, 0x2c000, v42
	s_nop 1
	v_addc_co_u32_e32 v49, vcc, 0, v43, vcc
	v_add_co_u32_e32 v50, vcc, 0x2e000, v42
	s_nop 1
	v_addc_co_u32_e32 v51, vcc, 0, v43, vcc
	global_load_dword v32, v[32:33], off nt
	s_nop 0
	global_load_dword v33, v[34:35], off nt
	s_nop 0
	global_load_dword v34, v[36:37], off nt
	global_load_dword v35, v[38:39], off nt
	s_nop 0
	global_load_dword v36, v[44:45], off nt
	global_load_dword v37, v[46:47], off nt
	global_load_dword v38, v[48:49], off nt
	global_load_dword v39, v[50:51], off nt
	v_add_co_u32_e32 v44, vcc, 0x30000, v42
	s_nop 1
	v_addc_co_u32_e32 v45, vcc, 0, v43, vcc
	v_add_co_u32_e32 v46, vcc, 0x32000, v42
	s_nop 1
	v_addc_co_u32_e32 v47, vcc, 0, v43, vcc
	v_add_co_u32_e32 v48, vcc, 0x34000, v42
	s_nop 1
	v_addc_co_u32_e32 v49, vcc, 0, v43, vcc
	v_add_co_u32_e32 v50, vcc, 0x36000, v42
	s_nop 1
	v_addc_co_u32_e32 v51, vcc, 0, v43, vcc
	v_add_co_u32_e32 v74, vcc, 0x38000, v42
	s_nop 1
	v_addc_co_u32_e32 v75, vcc, 0, v43, vcc
	v_add_co_u32_e32 v76, vcc, 0x3a000, v42
	s_nop 1
	v_addc_co_u32_e32 v77, vcc, 0, v43, vcc
	v_add_co_u32_e32 v78, vcc, 0x3c000, v42
	s_nop 1
	v_addc_co_u32_e32 v79, vcc, 0, v43, vcc
	v_add_co_u32_e32 v80, vcc, 0x3e000, v42
	s_nop 1
	v_addc_co_u32_e32 v81, vcc, 0, v43, vcc
	global_load_dword v42, v[44:45], off nt
	global_load_dword v43, v[46:47], off nt
	s_nop 0
	global_load_dword v44, v[48:49], off nt
	global_load_dword v45, v[50:51], off nt
	s_nop 0
	global_load_dword v48, v[74:75], off nt
	global_load_dword v49, v[76:77], off nt
	global_load_dword v46, v[78:79], off nt
	global_load_dword v47, v[80:81], off nt
	s_andn2_b64 vcc, exec, s[14:15]
	s_cbranch_vccnz .LBB0_99
; template <int MODE> __device__ __forceinline__ void wt_item(const float* W, int K, int N, int Np, const float* gain, bf16_t* WT, int item, float* scr, int lane) {
;     ...
;     if (gain) {
;         float gv[32];
; #pragma unroll
;         for (int i = 0; i < 32; ++i) gv[i] = gain[k0 + 2 * i + (lane >> 5)];
; #pragma unroll
;         for (int i = 0; i < 32; ++i) wv[i] *= gv[i];
	v_lshl_add_u64 v[40:41], v[40:41], 2, s[54:55]
	global_load_dword v50, v[40:41], off nt
	global_load_dword v51, v[40:41], off offset:8 nt
	global_load_dword v74, v[40:41], off offset:16 nt
	global_load_dword v75, v[40:41], off offset:24 nt
	global_load_dword v76, v[40:41], off offset:32 nt
	global_load_dword v77, v[40:41], off offset:40 nt
	global_load_dword v78, v[40:41], off offset:48 nt
	global_load_dword v79, v[40:41], off offset:56 nt
	global_load_dword v80, v[40:41], off offset:64 nt
	global_load_dword v81, v[40:41], off offset:72 nt
	global_load_dword v82, v[40:41], off offset:80 nt
	global_load_dword v83, v[40:41], off offset:88 nt
	global_load_dword v84, v[40:41], off offset:96 nt
	global_load_dword v85, v[40:41], off offset:104 nt
	global_load_dword v86, v[40:41], off offset:112 nt
	global_load_dword v87, v[40:41], off offset:120 nt
	global_load_dword v88, v[40:41], off offset:128 nt
	global_load_dword v89, v[40:41], off offset:136 nt
	global_load_dword v90, v[40:41], off offset:144 nt
	global_load_dword v91, v[40:41], off offset:152 nt
	global_load_dword v92, v[40:41], off offset:160 nt
	global_load_dword v93, v[40:41], off offset:168 nt
	global_load_dword v94, v[40:41], off offset:176 nt
	global_load_dword v95, v[40:41], off offset:184 nt
	global_load_dword v96, v[40:41], off offset:192 nt
	global_load_dword v97, v[40:41], off offset:200 nt
	global_load_dword v98, v[40:41], off offset:208 nt
	global_load_dword v99, v[40:41], off offset:216 nt
	global_load_dword v100, v[40:41], off offset:224 nt
	global_load_dword v101, v[40:41], off offset:232 nt
	global_load_dword v102, v[40:41], off offset:240 nt
	global_load_dword v103, v[40:41], off offset:248 nt
	s_waitcnt vmcnt(30)
	v_pk_mul_f32 v[16:17], v[16:17], v[50:51]
	s_waitcnt vmcnt(28)
	v_pk_mul_f32 v[18:19], v[18:19], v[74:75]
	s_waitcnt vmcnt(26)
	v_pk_mul_f32 v[20:21], v[20:21], v[76:77]
	s_waitcnt vmcnt(24)
	v_pk_mul_f32 v[22:23], v[22:23], v[78:79]
	s_waitcnt vmcnt(22)
	v_pk_mul_f32 v[24:25], v[24:25], v[80:81]
	s_waitcnt vmcnt(20)
	v_pk_mul_f32 v[26:27], v[26:27], v[82:83]
	s_waitcnt vmcnt(18)
	v_pk_mul_f32 v[28:29], v[28:29], v[84:85]
	s_waitcnt vmcnt(16)
	v_pk_mul_f32 v[30:31], v[30:31], v[86:87]
	s_waitcnt vmcnt(14)
	v_pk_mul_f32 v[32:33], v[32:33], v[88:89]
	s_waitcnt vmcnt(12)
	v_pk_mul_f32 v[34:35], v[34:35], v[90:91]
	s_waitcnt vmcnt(10)
	v_pk_mul_f32 v[36:37], v[36:37], v[92:93]
	s_waitcnt vmcnt(8)
	v_pk_mul_f32 v[38:39], v[38:39], v[94:95]
	s_waitcnt vmcnt(6)
	v_pk_mul_f32 v[42:43], v[42:43], v[96:97]
	s_waitcnt vmcnt(4)
	v_pk_mul_f32 v[44:45], v[44:45], v[98:99]
	s_waitcnt vmcnt(2)
	v_pk_mul_f32 v[48:49], v[48:49], v[100:101]
	s_waitcnt vmcnt(0)
	v_pk_mul_f32 v[46:47], v[46:47], v[102:103]

; __device__ __forceinline__ int orig_wgu(int np) { const int T = np >> 8, cl = np & 255; return ((cl >> 7) ? DFF : 0) + 128 * T + (cl & 127); }
; template <int MODE> __device__ __forceinline__ void wt_item(const float* W, int K, int N, int Np, const float* gain, bf16_t* WT, int item, float* scr, int lane) {
;     const int nblk = Np / 32, kb = item / nblk, nb = item - kb * nblk, k0 = 64 * kb, n0 = 32 * nb;
;     const int np = n0 + (lane & 31); const int o = (MODE == 1) ? orig_win(np) : (MODE == 2) ? orig_wgu(np) : np;
;     float wv[32];
; #pragma unroll
;     for (int i = 0; i < 32; ++i) { const int kk = 2 * i + (lane >> 5); wv[i] = (o >= 0) ? W[(size_t)(k0 + kk) * N + o] : 0.f; }
; __device__ __forceinline__ void ph0_prologue(const Ctx& C, unsigned char* lds) {
;     ...
;         if (r < I_OUT) { wt_item<0>(C.w_out, DM, DM, DM, nullptr, (bf16_t*)(C.ws + WS_WOUT), r, scr, C.lane); continue; } r -= I_OUT;
.LBB0_101:
	s_andn2_b64 vcc, exec, s[6:7]
	s_cbranch_vccnz .LBB0_103
	s_lshl_b32 s6, s20, 1
	s_and_b32 s6, s6, 0x1fc0
	s_add_i32 s8, s6, 0xfffff100
	s_lshl_b32 s6, s20, 5
	s_and_b32 s6, s6, 0x3e0
	v_or_b32_e32 v0, s6, v67
	v_add_u32_e32 v16, s8, v52
	v_readlane_b32 s52, v250, 39
	v_lshlrev_b32_e32 v0, 2, v0
	v_readlane_b32 s53, v250, 40
	v_ashrrev_i32_e32 v17, 31, v16
	v_lshlrev_b64 v[16:17], 12, v[16:17]
	v_lshl_add_u64 v[18:19], s[52:53], 0, v[0:1]
	v_lshl_add_u64 v[16:17], v[18:19], 0, v[16:17]
	v_add_co_u32_e32 v18, vcc, 0x2000, v16
	v_readlane_b32 s54, v250, 41
	s_nop 0
	v_addc_co_u32_e32 v19, vcc, 0, v17, vcc
	v_add_co_u32_e32 v20, vcc, 0x4000, v16
	v_readlane_b32 s55, v250, 42
	s_nop 0
	v_addc_co_u32_e32 v21, vcc, 0, v17, vcc
	v_add_co_u32_e32 v22, vcc, 0x6000, v16
	v_readlane_b32 s56, v250, 43
	s_nop 0
	v_addc_co_u32_e32 v23, vcc, 0, v17, vcc
	v_add_co_u32_e32 v24, vcc, 0x8000, v16
	v_readlane_b32 s57, v250, 44
	s_nop 0
	v_addc_co_u32_e32 v25, vcc, 0, v17, vcc
	v_add_co_u32_e32 v26, vcc, 0xa000, v16
	v_readlane_b32 s58, v250, 45
	s_nop 0
	v_addc_co_u32_e32 v27, vcc, 0, v17, vcc
	v_add_co_u32_e32 v28, vcc, 0xc000, v16
	v_readlane_b32 s59, v250, 46
	s_nop 0
	v_addc_co_u32_e32 v29, vcc, 0, v17, vcc
	v_add_co_u32_e32 v30, vcc, 0xe000, v16
	v_readlane_b32 s60, v250, 47
	s_nop 0
	v_addc_co_u32_e32 v31, vcc, 0, v17, vcc
	global_load_dword v0, v[16:17], off nt
	global_load_dword v34, v[18:19], off nt
	global_load_dword v35, v[20:21], off nt
	global_load_dword v36, v[22:23], off nt
	global_load_dword v37, v[24:25], off nt
	global_load_dword v38, v[26:27], off nt
	global_load_dword v39, v[28:29], off nt
	global_load_dword v40, v[30:31], off nt
	v_add_co_u32_e32 v18, vcc, 0x10000, v16
	v_readlane_b32 s61, v250, 48
	s_nop 0
	v_addc_co_u32_e32 v19, vcc, 0, v17, vcc
	v_add_co_u32_e32 v20, vcc, 0x12000, v16
	v_readlane_b32 s62, v250, 49
	s_nop 0
	v_addc_co_u32_e32 v21, vcc, 0, v17, vcc
	v_add_co_u32_e32 v22, vcc, 0x14000, v16
	v_readlane_b32 s63, v250, 50
	s_nop 0
	v_addc_co_u32_e32 v23, vcc, 0, v17, vcc
	v_add_co_u32_e32 v24, vcc, 0x16000, v16
	v_readlane_b32 s64, v250, 51
	s_nop 0
	v_addc_co_u32_e32 v25, vcc, 0, v17, vcc
	v_add_co_u32_e32 v26, vcc, 0x18000, v16
	v_readlane_b32 s65, v250, 52
	s_nop 0
	v_addc_co_u32_e32 v27, vcc, 0, v17, vcc
	v_add_co_u32_e32 v28, vcc, 0x1a000, v16
	v_readlane_b32 s66, v250, 53
	s_nop 0
	v_addc_co_u32_e32 v29, vcc, 0, v17, vcc
	v_add_co_u32_e32 v30, vcc, 0x1c000, v16
	v_readlane_b32 s67, v250, 54
	s_nop 0
	v_addc_co_u32_e32 v31, vcc, 0, v17, vcc
	v_add_co_u32_e32 v32, vcc, 0x1e000, v16
	s_nop 1
	v_addc_co_u32_e32 v33, vcc, 0, v17, vcc
	global_load_dword v41, v[18:19], off nt
	global_load_dword v42, v[20:21], off nt
	global_load_dword v43, v[22:23], off nt
	global_load_dword v44, v[24:25], off nt
	global_load_dword v45, v[26:27], off nt
	global_load_dword v46, v[28:29], off nt
	global_load_dword v47, v[30:31], off nt
	global_load_dword v48, v[32:33], off nt
	v_add_co_u32_e32 v18, vcc, 0x20000, v16
	s_nop 1
	v_addc_co_u32_e32 v19, vcc, 0, v17, vcc
	v_add_co_u32_e32 v20, vcc, 0x22000, v16
	s_nop 1
	v_addc_co_u32_e32 v21, vcc, 0, v17, vcc
	v_add_co_u32_e32 v22, vcc, 0x24000, v16
	s_nop 1
	v_addc_co_u32_e32 v23, vcc, 0, v17, vcc
	v_add_co_u32_e32 v24, vcc, 0x26000, v16
	s_nop 1
	v_addc_co_u32_e32 v25, vcc, 0, v17, vcc
	v_add_co_u32_e32 v26, vcc, 0x28000, v16
	s_nop 1
	v_addc_co_u32_e32 v27, vcc, 0, v17, vcc
	v_add_co_u32_e32 v28, vcc, 0x2a000, v16
	s_nop 1
	v_addc_co_u32_e32 v29, vcc, 0, v17, vcc
	v_add_co_u32_e32 v30, vcc, 0x2c000, v16
	s_nop 1
	v_addc_co_u32_e32 v31, vcc, 0, v17, vcc
	v_add_co_u32_e32 v32, vcc, 0x2e000, v16
	s_nop 1
	v_addc_co_u32_e32 v33, vcc, 0, v17, vcc
	global_load_dword v49, v[18:19], off nt
	global_load_dword v50, v[20:21], off nt
	global_load_dword v51, v[22:23], off nt
	global_load_dword v74, v[24:25], off nt
	global_load_dword v75, v[26:27], off nt
	global_load_dword v76, v[28:29], off nt
	global_load_dword v77, v[30:31], off nt
	s_nop 0
	global_load_dword v32, v[32:33], off nt
	v_add_co_u32_e32 v18, vcc, 0x30000, v16
	s_nop 1
	v_addc_co_u32_e32 v19, vcc, 0, v17, vcc
	v_add_co_u32_e32 v20, vcc, 0x32000, v16
	s_nop 1
	v_addc_co_u32_e32 v21, vcc, 0, v17, vcc
	v_add_co_u32_e32 v22, vcc, 0x34000, v16
	s_nop 1
	v_addc_co_u32_e32 v23, vcc, 0, v17, vcc
	v_add_co_u32_e32 v24, vcc, 0x36000, v16
	s_nop 1
	v_addc_co_u32_e32 v25, vcc, 0, v17, vcc
	v_add_co_u32_e32 v26, vcc, 0x38000, v16
	s_nop 1
	v_addc_co_u32_e32 v27, vcc, 0, v17, vcc
	v_add_co_u32_e32 v28, vcc, 0x3a000, v16
	s_nop 1
	v_addc_co_u32_e32 v29, vcc, 0, v17, vcc
	v_add_co_u32_e32 v30, vcc, 0x3c000, v16
	s_nop 1
	v_addc_co_u32_e32 v31, vcc, 0, v17, vcc
	v_add_co_u32_e32 v16, vcc, 0x3e000, v16
	s_nop 1
	v_addc_co_u32_e32 v17, vcc, 0, v17, vcc
	global_load_dword v18, v[18:19], off nt
	s_nop 0
	global_load_dword v19, v[20:21], off nt
	s_nop 0
	global_load_dword v20, v[22:23], off nt
	global_load_dword v21, v[24:25], off nt
	s_nop 0
	global_load_dword v22, v[26:27], off nt
	global_load_dword v23, v[28:29], off nt
	global_load_dword v24, v[30:31], off nt
	s_nop 0
	global_load_dword v16, v[16:17], off nt
	s_waitcnt vmcnt(30)
; __device__ __forceinline__ unsigned cvt_pk_bf16(float lo, float hi) { unsigned r; asm volatile("v_cvt_pk_bf16_f32 %0, %1, %2" : "=v"(r) : "v"(lo), "v"(hi)); return r; }
; #define LDS_WAIT() asm volatile("s_waitcnt lgkmcnt(0)" ::: "memory")
; template <int MODE> __device__ __forceinline__ void wt_item(const float* W, int K, int N, int Np, const float* gain, bf16_t* WT, int item, float* scr, int lane) {
;     ...
;     for (int i = 0; i < 32; ++i) scr[(2 * i + (lane >> 5)) * 33 + (lane & 31)] = wv[i];
;     LDS_WAIT();
;     const int c = lane & 7;
; #pragma unroll
;     for (int j = 0; j < 4; ++j) { const int n = (lane >> 3) + 8 * j; const float* s = scr + (8 * c) * 33 + n;
;         u32x4 ov; ov.x = cvt_pk_bf16(s[0 * 33], s[1 * 33]); ov.y = cvt_pk_bf16(s[2 * 33], s[3 * 33]); ov.z = cvt_pk_bf16(s[4 * 33], s[5 * 33]); ov.w = cvt_pk_bf16(s[6 * 33], s[7 * 33]);
;         *(u32x4*)(WT + (size_t)(n0 + n) * K + k0 + 8 * c) = ov; }
;     LDS_WAIT();
	ds_write2_b32 v53, v0, v34 offset1:66
	s_waitcnt vmcnt(28)
	ds_write2_b32 v53, v35, v36 offset0:132 offset1:198
	s_waitcnt vmcnt(26)
	ds_write2_b32 v61, v37, v38 offset0:8 offset1:74
	s_waitcnt vmcnt(24)
	ds_write2_b32 v61, v39, v40 offset0:140 offset1:206
	s_waitcnt vmcnt(22)
	ds_write2_b32 v62, v41, v42 offset0:16 offset1:82
	s_waitcnt vmcnt(20)
	ds_write2_b32 v62, v43, v44 offset0:148 offset1:214
	s_waitcnt vmcnt(18)
	ds_write2_b32 v63, v45, v46 offset0:24 offset1:90
	s_waitcnt vmcnt(16)
	ds_write2_b32 v63, v47, v48 offset0:156 offset1:222
	s_waitcnt vmcnt(14)
	ds_write2_b32 v65, v49, v50 offset0:32 offset1:98
	s_waitcnt vmcnt(12)
	ds_write2_b32 v65, v51, v74 offset0:164 offset1:230
	s_waitcnt vmcnt(10)
	ds_write2_b32 v68, v75, v76 offset0:40 offset1:106
	s_waitcnt vmcnt(8)
	ds_write2_b32 v68, v77, v32 offset0:172 offset1:238
	s_waitcnt vmcnt(6)
	ds_write2_b32 v69, v18, v19 offset0:48 offset1:114
	s_waitcnt vmcnt(4)
	ds_write2_b32 v69, v20, v21 offset0:180 offset1:246
	s_waitcnt vmcnt(2)
	ds_write2_b32 v70, v22, v23 offset0:56 offset1:122
	s_waitcnt vmcnt(0)
	ds_write2_b32 v70, v24, v16 offset0:188 offset1:254
	s_waitcnt lgkmcnt(0)
	ds_read2_b32 v[16:17], v55 offset1:33
	s_waitcnt lgkmcnt(0)
	v_cvt_pk_bf16_f32 v16, v16, v17
	ds_read2_b32 v[18:19], v55 offset0:66 offset1:99
	s_waitcnt lgkmcnt(0)
	v_cvt_pk_bf16_f32 v17, v18, v19
	ds_read2_b32 v[18:19], v55 offset0:132 offset1:165
	s_waitcnt lgkmcnt(0)
	v_cvt_pk_bf16_f32 v18, v18, v19
	ds_read2_b32 v[20:21], v55 offset0:198 offset1:231
	s_waitcnt lgkmcnt(0)
	v_cvt_pk_bf16_f32 v19, v20, v21
	v_add_u32_e32 v20, s6, v54
	v_ashrrev_i32_e32 v21, 31, v20
	v_lshl_add_u64 v[22:23], s[8:9], 1, v[12:13]
	v_lshlrev_b64 v[20:21], 11, v[20:21]
	v_lshl_add_u64 v[20:21], v[22:23], 0, v[20:21]
	ds_read2_b32 v[24:25], v55 offset0:8 offset1:41
	global_store_dwordx4 v[20:21], v[16:19], off
	s_waitcnt lgkmcnt(0)
	s_nop 0
	v_cvt_pk_bf16_f32 v16, v24, v25
	ds_read2_b32 v[18:19], v55 offset0:74 offset1:107
	s_waitcnt lgkmcnt(0)
	v_cvt_pk_bf16_f32 v17, v18, v19
	ds_read2_b32 v[18:19], v55 offset0:140 offset1:173
	s_waitcnt lgkmcnt(0)
	v_cvt_pk_bf16_f32 v18, v18, v19
	ds_read2_b32 v[20:21], v55 offset0:206 offset1:239
	s_waitcnt lgkmcnt(0)
	v_cvt_pk_bf16_f32 v19, v20, v21
	v_add_u32_e32 v20, s6, v56
	v_ashrrev_i32_e32 v21, 31, v20
	v_lshlrev_b64 v[20:21], 11, v[20:21]
	v_lshl_add_u64 v[20:21], v[22:23], 0, v[20:21]
	ds_read2_b32 v[24:25], v55 offset0:16 offset1:49
	global_store_dwordx4 v[20:21], v[16:19], off
	s_waitcnt lgkmcnt(0)
	s_nop 0
	v_cvt_pk_bf16_f32 v16, v24, v25
	ds_read2_b32 v[18:19], v55 offset0:82 offset1:115
	s_waitcnt lgkmcnt(0)
	v_cvt_pk_bf16_f32 v17, v18, v19
	ds_read2_b32 v[18:19], v55 offset0:148 offset1:181
	s_waitcnt lgkmcnt(0)
	v_cvt_pk_bf16_f32 v18, v18, v19
	ds_read2_b32 v[20:21], v55 offset0:214 offset1:247
	s_waitcnt lgkmcnt(0)
	v_cvt_pk_bf16_f32 v19, v20, v21
	v_add_u32_e32 v20, s6, v57
	v_ashrrev_i32_e32 v21, 31, v20
	v_lshlrev_b64 v[20:21], 11, v[20:21]
	v_lshl_add_u64 v[20:21], v[22:23], 0, v[20:21]
	ds_read2_b32 v[24:25], v55 offset0:24 offset1:57
	global_store_dwordx4 v[20:21], v[16:19], off
	s_waitcnt lgkmcnt(0)
	s_nop 0
	v_cvt_pk_bf16_f32 v16, v24, v25
	ds_read2_b32 v[18:19], v55 offset0:90 offset1:123
	s_waitcnt lgkmcnt(0)
	v_cvt_pk_bf16_f32 v17, v18, v19
	ds_read2_b32 v[18:19], v55 offset0:156 offset1:189
	s_waitcnt lgkmcnt(0)
	v_cvt_pk_bf16_f32 v18, v18, v19
	ds_read2_b32 v[20:21], v55 offset0:222 offset1:255
	s_waitcnt lgkmcnt(0)
	v_cvt_pk_bf16_f32 v19, v20, v21
	v_add_u32_e32 v20, s6, v58
	v_ashrrev_i32_e32 v21, 31, v20
	v_lshlrev_b64 v[20:21], 11, v[20:21]
	v_lshl_add_u64 v[20:21], v[22:23], 0, v[20:21]
	global_store_dwordx4 v[20:21], v[16:19], off
	s_waitcnt lgkmcnt(0)

; __device__ __forceinline__ int orig_wgu(int np) { const int T = np >> 8, cl = np & 255; return ((cl >> 7) ? DFF : 0) + 128 * T + (cl & 127); }
; template <int MODE> __device__ __forceinline__ void wt_item(const float* W, int K, int N, int Np, const float* gain, bf16_t* WT, int item, float* scr, int lane) {
;     ...
;     const int np = n0 + (lane & 31); const int o = (MODE == 1) ? orig_win(np) : (MODE == 2) ? orig_wgu(np) : np;
;     float wv[32];
; #pragma unroll
;     for (int i = 0; i < 32; ++i) { const int kk = 2 * i + (lane >> 5); wv[i] = (o >= 0) ? W[(size_t)(k0 + kk) * N + o] : 0.f; }
.LBB0_126:
	v_readlane_b32 s52, v250, 23
	s_lshl_b32 s6, s16, 6
	v_readlane_b32 s60, v250, 31
	v_readlane_b32 s61, v250, 32
	v_cmp_lt_i32_e32 vcc, -1, v0
	v_add_u32_e32 v32, s6, v52
	v_lshl_add_u64 v[38:39], v[0:1], 2, s[60:61]
	v_mov_b32_e32 v17, 0
	v_mov_b32_e32 v16, 0
	v_readlane_b32 s53, v250, 24
	v_readlane_b32 s54, v250, 25
	v_readlane_b32 s55, v250, 26
	v_readlane_b32 s56, v250, 27
	v_readlane_b32 s57, v250, 28
	v_readlane_b32 s58, v250, 29
	v_readlane_b32 s59, v250, 30
	v_readlane_b32 s62, v250, 33
	v_readlane_b32 s63, v250, 34
	v_readlane_b32 s64, v250, 35
	v_readlane_b32 s65, v250, 36
	v_readlane_b32 s66, v250, 37
	v_readlane_b32 s67, v250, 38
	s_and_saveexec_b64 s[16:17], vcc
	s_cbranch_execz .LBB0_128
	v_mad_i64_i32 v[18:19], s[22:23], v32, s19, v[38:39]
	global_load_dword v16, v[18:19], off nt
.LBB0_128:
	s_or_b64 exec, exec, s[16:17]
	s_and_saveexec_b64 s[16:17], vcc
	s_cbranch_execz .LBB0_130
	v_add_u32_e32 v0, 2, v32
	v_mad_i64_i32 v[18:19], s[22:23], v0, s19, v[38:39]
	global_load_dword v17, v[18:19], off nt
.LBB0_130:
	s_or_b64 exec, exec, s[16:17]
	v_mov_b32_e32 v19, 0
	v_mov_b32_e32 v18, 0
	s_and_saveexec_b64 s[16:17], vcc
	s_cbranch_execz .LBB0_132
	v_add_u32_e32 v0, 4, v32
	v_mad_i64_i32 v[20:21], s[22:23], v0, s19, v[38:39]
	global_load_dword v18, v[20:21], off nt
.LBB0_132:
	s_or_b64 exec, exec, s[16:17]
	s_and_saveexec_b64 s[16:17], vcc
	s_cbranch_execz .LBB0_134
	v_add_u32_e32 v0, 6, v32
	v_mad_i64_i32 v[20:21], s[22:23], v0, s19, v[38:39]
	global_load_dword v19, v[20:21], off nt
.LBB0_134:
	s_or_b64 exec, exec, s[16:17]
	v_mov_b32_e32 v21, 0
	v_mov_b32_e32 v20, 0
	s_and_saveexec_b64 s[16:17], vcc
	s_cbranch_execz .LBB0_136
	v_add_u32_e32 v0, 8, v32
	v_mad_i64_i32 v[22:23], s[22:23], v0, s19, v[38:39]
	global_load_dword v20, v[22:23], off nt
.LBB0_136:
	s_or_b64 exec, exec, s[16:17]
	s_and_saveexec_b64 s[16:17], vcc
	s_cbranch_execz .LBB0_138
	v_add_u32_e32 v0, 10, v32
	v_mad_i64_i32 v[22:23], s[22:23], v0, s19, v[38:39]
	global_load_dword v21, v[22:23], off nt
.LBB0_138:
	s_or_b64 exec, exec, s[16:17]
	v_mov_b32_e32 v23, 0
	v_mov_b32_e32 v22, 0
	s_and_saveexec_b64 s[16:17], vcc
	s_cbranch_execz .LBB0_140
	v_add_u32_e32 v0, 12, v32
	v_mad_i64_i32 v[24:25], s[22:23], v0, s19, v[38:39]
	global_load_dword v22, v[24:25], off nt
.LBB0_140:
	s_or_b64 exec, exec, s[16:17]
	s_and_saveexec_b64 s[16:17], vcc
	s_cbranch_execz .LBB0_142
	v_add_u32_e32 v0, 14, v32
	v_mad_i64_i32 v[24:25], s[22:23], v0, s19, v[38:39]
	global_load_dword v23, v[24:25], off nt
.LBB0_142:
	s_or_b64 exec, exec, s[16:17]
	v_mov_b32_e32 v25, 0
	v_mov_b32_e32 v24, 0
	s_and_saveexec_b64 s[16:17], vcc
	s_cbranch_execz .LBB0_144
	v_add_u32_e32 v0, 16, v32
	v_mad_i64_i32 v[26:27], s[22:23], v0, s19, v[38:39]
	global_load_dword v24, v[26:27], off nt
.LBB0_144:
	s_or_b64 exec, exec, s[16:17]
	s_and_saveexec_b64 s[16:17], vcc
	s_cbranch_execz .LBB0_146
	v_add_u32_e32 v0, 18, v32
	v_mad_i64_i32 v[26:27], s[22:23], v0, s19, v[38:39]
	global_load_dword v25, v[26:27], off nt
.LBB0_146:
	s_or_b64 exec, exec, s[16:17]
	v_mov_b32_e32 v27, 0
	v_mov_b32_e32 v26, 0
	s_and_saveexec_b64 s[16:17], vcc
	s_cbranch_execz .LBB0_148
	v_add_u32_e32 v0, 20, v32
	v_mad_i64_i32 v[28:29], s[22:23], v0, s19, v[38:39]
	global_load_dword v26, v[28:29], off nt
.LBB0_148:
	s_or_b64 exec, exec, s[16:17]
	s_and_saveexec_b64 s[16:17], vcc
	s_cbranch_execz .LBB0_150
	v_add_u32_e32 v0, 22, v32
	v_mad_i64_i32 v[28:29], s[22:23], v0, s19, v[38:39]
	global_load_dword v27, v[28:29], off nt
.LBB0_150:
	s_or_b64 exec, exec, s[16:17]
	v_mov_b32_e32 v29, 0
	v_mov_b32_e32 v28, 0
	s_and_saveexec_b64 s[16:17], vcc
	s_cbranch_execz .LBB0_152
	v_add_u32_e32 v0, 24, v32
	v_mad_i64_i32 v[30:31], s[22:23], v0, s19, v[38:39]
	global_load_dword v28, v[30:31], off nt
.LBB0_152:
	s_or_b64 exec, exec, s[16:17]
	s_and_saveexec_b64 s[16:17], vcc
	s_cbranch_execz .LBB0_154
	v_add_u32_e32 v0, 26, v32
	v_mad_i64_i32 v[30:31], s[22:23], v0, s19, v[38:39]
	global_load_dword v29, v[30:31], off nt
; template <int MODE> __device__ __forceinline__ void wt_item(const float* W, int K, int N, int Np, const float* gain, bf16_t* WT, int item, float* scr, int lane) {
;     ...
;     for (int i = 0; i < 32; ++i) { const int kk = 2 * i + (lane >> 5); wv[i] = (o >= 0) ? W[(size_t)(k0 + kk) * N + o] : 0.f; }
.LBB0_154:
	s_or_b64 exec, exec, s[16:17]
	v_mov_b32_e32 v31, 0
	v_mov_b32_e32 v30, 0
	s_and_saveexec_b64 s[16:17], vcc
	s_cbranch_execz .LBB0_156
	v_add_u32_e32 v0, 28, v32
	v_mad_i64_i32 v[34:35], s[22:23], v0, s19, v[38:39]
	global_load_dword v30, v[34:35], off nt
.LBB0_156:
	s_or_b64 exec, exec, s[16:17]
	s_and_saveexec_b64 s[16:17], vcc
	s_cbranch_execz .LBB0_158
	v_add_u32_e32 v0, 30, v32
	v_mad_i64_i32 v[34:35], s[22:23], v0, s19, v[38:39]
	global_load_dword v31, v[34:35], off nt
.LBB0_158:
	s_or_b64 exec, exec, s[16:17]
	v_mov_b32_e32 v35, 0
	v_mov_b32_e32 v34, 0
	s_and_saveexec_b64 s[16:17], vcc
	s_cbranch_execz .LBB0_160
	v_add_u32_e32 v0, 32, v32
	v_mad_i64_i32 v[36:37], s[22:23], v0, s19, v[38:39]
	global_load_dword v34, v[36:37], off nt
.LBB0_160:
	s_or_b64 exec, exec, s[16:17]
	s_and_saveexec_b64 s[16:17], vcc
	s_cbranch_execz .LBB0_162
	v_add_u32_e32 v0, 34, v32
	v_mad_i64_i32 v[36:37], s[22:23], v0, s19, v[38:39]
	global_load_dword v35, v[36:37], off nt
.LBB0_162:
	s_or_b64 exec, exec, s[16:17]
	v_mov_b32_e32 v37, 0
	v_mov_b32_e32 v36, 0
	s_and_saveexec_b64 s[16:17], vcc
	s_cbranch_execz .LBB0_164
	v_add_u32_e32 v0, 36, v32
	v_mad_i64_i32 v[40:41], s[22:23], v0, s19, v[38:39]
	global_load_dword v36, v[40:41], off nt
.LBB0_164:
	s_or_b64 exec, exec, s[16:17]
	s_and_saveexec_b64 s[16:17], vcc
	s_cbranch_execz .LBB0_166
	v_add_u32_e32 v0, 38, v32
	v_mad_i64_i32 v[40:41], s[22:23], v0, s19, v[38:39]
	global_load_dword v37, v[40:41], off nt
.LBB0_166:
	s_or_b64 exec, exec, s[16:17]
	v_mov_b32_e32 v41, 0
	v_mov_b32_e32 v40, 0
	s_and_saveexec_b64 s[16:17], vcc
	s_cbranch_execz .LBB0_168
	v_add_u32_e32 v0, 40, v32
	v_mad_i64_i32 v[42:43], s[22:23], v0, s19, v[38:39]
	global_load_dword v40, v[42:43], off nt
.LBB0_168:
	s_or_b64 exec, exec, s[16:17]
	s_and_saveexec_b64 s[16:17], vcc
	s_cbranch_execz .LBB0_170
	v_add_u32_e32 v0, 42, v32
	v_mad_i64_i32 v[42:43], s[22:23], v0, s19, v[38:39]
	global_load_dword v41, v[42:43], off nt
.LBB0_170:
	s_or_b64 exec, exec, s[16:17]
	v_mov_b32_e32 v43, 0
	v_mov_b32_e32 v42, 0
	s_and_saveexec_b64 s[16:17], vcc
	s_cbranch_execz .LBB0_172
	v_add_u32_e32 v0, 44, v32
	v_mad_i64_i32 v[44:45], s[22:23], v0, s19, v[38:39]
	global_load_dword v42, v[44:45], off nt
.LBB0_172:
	s_or_b64 exec, exec, s[16:17]
	s_and_saveexec_b64 s[16:17], vcc
	s_cbranch_execz .LBB0_174
	v_add_u32_e32 v0, 46, v32
	v_mad_i64_i32 v[44:45], s[22:23], v0, s19, v[38:39]
	global_load_dword v43, v[44:45], off nt
.LBB0_174:
	s_or_b64 exec, exec, s[16:17]
	v_mov_b32_e32 v45, 0
	v_mov_b32_e32 v44, 0
	s_and_saveexec_b64 s[16:17], vcc
	s_cbranch_execz .LBB0_176
	v_add_u32_e32 v0, 48, v32
	v_mad_i64_i32 v[46:47], s[22:23], v0, s19, v[38:39]
	global_load_dword v44, v[46:47], off nt
.LBB0_176:
	s_or_b64 exec, exec, s[16:17]
	s_and_saveexec_b64 s[16:17], vcc
	s_cbranch_execz .LBB0_178
	v_add_u32_e32 v0, 50, v32
	v_mad_i64_i32 v[46:47], s[22:23], v0, s19, v[38:39]
	global_load_dword v45, v[46:47], off nt
.LBB0_178:
	s_or_b64 exec, exec, s[16:17]
	v_mov_b32_e32 v47, 0
	v_mov_b32_e32 v46, 0
	s_and_saveexec_b64 s[16:17], vcc
	s_cbranch_execz .LBB0_180
	v_add_u32_e32 v0, 52, v32
	v_mad_i64_i32 v[48:49], s[22:23], v0, s19, v[38:39]
	global_load_dword v46, v[48:49], off nt
.LBB0_180:
	s_or_b64 exec, exec, s[16:17]
	s_and_saveexec_b64 s[16:17], vcc
	s_cbranch_execz .LBB0_182
	v_add_u32_e32 v0, 54, v32
	v_mad_i64_i32 v[48:49], s[22:23], v0, s19, v[38:39]
	global_load_dword v47, v[48:49], off nt
.LBB0_182:
	s_or_b64 exec, exec, s[16:17]
	v_mov_b32_e32 v49, 0
	v_mov_b32_e32 v48, 0
	s_and_saveexec_b64 s[16:17], vcc
	s_cbranch_execz .LBB0_184
	v_add_u32_e32 v0, 56, v32
	v_mad_i64_i32 v[50:51], s[22:23], v0, s19, v[38:39]
	global_load_dword v48, v[50:51], off nt
.LBB0_184:
	s_or_b64 exec, exec, s[16:17]
	s_and_saveexec_b64 s[16:17], vcc
	s_cbranch_execz .LBB0_186
	v_add_u32_e32 v0, 58, v32
	v_mad_i64_i32 v[50:51], s[22:23], v0, s19, v[38:39]
	global_load_dword v49, v[50:51], off nt

; template <int MODE> __device__ __forceinline__ void wt_item(const float* W, int K, int N, int Np, const float* gain, bf16_t* WT, int item, float* scr, int lane) {
;     ...
;     for (int i = 0; i < 32; ++i) { const int kk = 2 * i + (lane >> 5); wv[i] = (o >= 0) ? W[(size_t)(k0 + kk) * N + o] : 0.f; }
;     if (gain) {
;         float gv[32];
; #pragma unroll
;         for (int i = 0; i < 32; ++i) gv[i] = gain[k0 + 2 * i + (lane >> 5)];
; #pragma unroll
;         for (int i = 0; i < 32; ++i) wv[i] *= gv[i];
; __device__ __forceinline__ void ph0_prologue(const Ctx& C, unsigned char* lds) {
;     ...
;     for (int it = gw; it < NIT; it += NGW) {
.LBB0_189:
	v_add_u32_e32 v0, 60, v32
	v_mad_i64_i32 v[74:75], s[22:23], v0, s19, v[38:39]
	global_load_dword v50, v[74:75], off nt
	s_or_b64 exec, exec, s[16:17]
	s_and_saveexec_b64 s[16:17], vcc
	s_cbranch_execz .LBB0_188
.LBB0_190:
	v_add_u32_e32 v0, 62, v32
	v_mad_i64_i32 v[38:39], s[22:23], v0, s19, v[38:39]
	global_load_dword v51, v[38:39], off nt
	s_or_b64 exec, exec, s[16:17]
	s_andn2_b64 vcc, exec, s[80:81]
	s_cbranch_vccnz .LBB0_9
.LBB0_191:
	v_readlane_b32 s52, v250, 23
	v_ashrrev_i32_e32 v33, 31, v32
	v_readlane_b32 s58, v250, 29
	v_readlane_b32 s59, v250, 30
	v_readlane_b32 s53, v250, 24
	v_readlane_b32 s54, v250, 25
	v_lshl_add_u64 v[32:33], v[32:33], 2, s[58:59]
	global_load_dword v38, v[32:33], off nt
	global_load_dword v39, v[32:33], off offset:8 nt
	global_load_dword v74, v[32:33], off offset:16 nt
	global_load_dword v75, v[32:33], off offset:24 nt
	global_load_dword v76, v[32:33], off offset:32 nt
	global_load_dword v77, v[32:33], off offset:40 nt
	global_load_dword v78, v[32:33], off offset:48 nt
	global_load_dword v79, v[32:33], off offset:56 nt
	global_load_dword v80, v[32:33], off offset:64 nt
	global_load_dword v81, v[32:33], off offset:72 nt
	global_load_dword v82, v[32:33], off offset:80 nt
	global_load_dword v83, v[32:33], off offset:88 nt
	global_load_dword v84, v[32:33], off offset:96 nt
	global_load_dword v85, v[32:33], off offset:104 nt
	global_load_dword v86, v[32:33], off offset:112 nt
	global_load_dword v87, v[32:33], off offset:120 nt
	global_load_dword v88, v[32:33], off offset:128 nt
	global_load_dword v89, v[32:33], off offset:136 nt
	global_load_dword v90, v[32:33], off offset:144 nt
	global_load_dword v91, v[32:33], off offset:152 nt
	global_load_dword v92, v[32:33], off offset:160 nt
	global_load_dword v93, v[32:33], off offset:168 nt
	global_load_dword v94, v[32:33], off offset:176 nt
	global_load_dword v95, v[32:33], off offset:184 nt
	global_load_dword v96, v[32:33], off offset:192 nt
	global_load_dword v97, v[32:33], off offset:200 nt
	global_load_dword v98, v[32:33], off offset:208 nt
	global_load_dword v99, v[32:33], off offset:216 nt
	global_load_dword v100, v[32:33], off offset:224 nt
	global_load_dword v101, v[32:33], off offset:232 nt
	global_load_dword v102, v[32:33], off offset:240 nt
	global_load_dword v103, v[32:33], off offset:248 nt
	v_readlane_b32 s55, v250, 26
	v_readlane_b32 s56, v250, 27
	v_readlane_b32 s57, v250, 28
	v_readlane_b32 s60, v250, 31
	v_readlane_b32 s61, v250, 32
	v_readlane_b32 s62, v250, 33
	v_readlane_b32 s63, v250, 34
	v_readlane_b32 s64, v250, 35
	v_readlane_b32 s65, v250, 36
	v_readlane_b32 s66, v250, 37
	v_readlane_b32 s67, v250, 38
	s_waitcnt vmcnt(30)
	v_pk_mul_f32 v[16:17], v[16:17], v[38:39]
	s_waitcnt vmcnt(28)
	v_pk_mul_f32 v[18:19], v[18:19], v[74:75]
	s_waitcnt vmcnt(26)
	v_pk_mul_f32 v[20:21], v[20:21], v[76:77]
	s_waitcnt vmcnt(24)
	v_pk_mul_f32 v[22:23], v[22:23], v[78:79]
	s_waitcnt vmcnt(22)
	v_pk_mul_f32 v[24:25], v[24:25], v[80:81]
	s_waitcnt vmcnt(20)
	v_pk_mul_f32 v[26:27], v[26:27], v[82:83]
	s_waitcnt vmcnt(18)
	v_pk_mul_f32 v[28:29], v[28:29], v[84:85]
	s_waitcnt vmcnt(16)
	v_pk_mul_f32 v[30:31], v[30:31], v[86:87]
	s_waitcnt vmcnt(14)
	v_pk_mul_f32 v[34:35], v[34:35], v[88:89]
	s_waitcnt vmcnt(12)
	v_pk_mul_f32 v[36:37], v[36:37], v[90:91]
	s_waitcnt vmcnt(10)
	v_pk_mul_f32 v[40:41], v[40:41], v[92:93]
	s_waitcnt vmcnt(8)
	v_pk_mul_f32 v[42:43], v[42:43], v[94:95]
	s_waitcnt vmcnt(6)
	v_pk_mul_f32 v[44:45], v[44:45], v[96:97]
	s_waitcnt vmcnt(4)
	v_pk_mul_f32 v[46:47], v[46:47], v[98:99]
	s_waitcnt vmcnt(2)
	v_pk_mul_f32 v[48:49], v[48:49], v[100:101]
	s_waitcnt vmcnt(0)
	v_pk_mul_f32 v[50:51], v[50:51], v[102:103]
	s_branch .LBB0_9
